# stack3 plus removal of the redundant second accumulator zero-init run (127 v_mov per tile per wave) ahead of every GEMM K-loop
# baseline (speedup 1.0000x reference)
; #define PG8_STAGE(bufoff, gbase, voff) do { _Pragma("unroll") for (int _i = 0; _i < 2; ++_i) \
;         __builtin_amdgcn_global_load_lds((const unsigned*)((const char*)(gbase) + (voff)[_i]), (LAS unsigned*)(lds + (bufoff) + ldsw + _i * 8192), 16, 0, 0); } while (0)
; #define PG8_LDA(dst, b, h) do { _Pragma("unroll") for (int m = 0; m < 4; ++m) _Pragma("unroll") for (int k = 0; k < 2; ++k) dst[m][k] = *(const LAS bf16x8*)(lds + PG8_SA(b, h) + aoff + m * 2048 + k * 1024); } while (0)
; #define PG8_LDB(dst, b, h) do { _Pragma("unroll") for (int n = 0; n < 2; ++n) _Pragma("unroll") for (int k = 0; k < 2; ++k) dst[n][k] = *(const LAS bf16x8*)(lds + PG8_SB(b, h) + boff + n * 2048 + k * 1024); } while (0)
; #define PG8_MMA(ai, bj, At, Bt) do { __builtin_amdgcn_s_setprio(1); _Pragma("unroll") for (int m = 0; m < 4; ++m) _Pragma("unroll") for (int n = 0; n < 2; ++n) _Pragma("unroll") for (int k = 0; k < 2; ++k) \
;         acc[ai][bj][m][n] = __builtin_amdgcn_mfma_f32_16x16x32_bf16(Bt[n][k], At[m][k], acc[ai][bj][m][n], 0, 0, 0); __builtin_amdgcn_s_setprio(0); } while (0)
; template <class Epi>
; DI void gemm_phase(LAS unsigned char* lds, const Gemm g, const StaticOrder& S, const Epi& E) {
;     ...
;     f32x4 acc[2][2][4][2];
; #pragma unroll
;     for (int a = 0; a < 2; ++a)
; #pragma unroll
;         for (int b = 0; b < 2; ++b)
; #pragma unroll
;             for (int m = 0; m < 4; ++m)
; #pragma unroll
;                 for (int n = 0; n < 2; ++n) acc[a][b][m][n] = (f32x4){0.f, 0.f, 0.f, 0.f};
;     ...
;     for (;;) {
;         const bool has_next = S.next(ui + 1, nxt);
;         const char* nA = has_next ? (const char*)g.A + (size_t)nxt.pm * tstepA + PG8_KOFF(nxt) : cA; const char* nB = has_next ? (const char*)g.Bt + (size_t)nxt.pn * tstepB + PG8_KOFF(nxt) : cB;
;         for (int t = 0; t < nt; t += 2) {
;             const bool last = (t == nt - 2);
;             const char* a1 = cA + (size_t)(t + 1) * kstep;
;             const char* a2 = last ? nA : cA + (size_t)(t + 2) * kstep; const char* b2 = last ? nB : cB + (size_t)(t + 2) * kstep;
;             const char* a3 = a2 + kstep; const char* b3 = b2 + kstep;
;             PG8_LDB(B0, 0, 0); PG8_LDB(B1, 0, 1); PG8_SCHED; PG8_LDA(At, 0, 0); PG8_STAGE(PG8_SA(1, 1), a1 + hstepA, voffA);
;             PG8_WAIT_V(8); PG8_WAIT_L(0); PG8_BAR; PG8_MMA(0, 0, At, B0); PG8_MMA(0, 1, At, B1); PG8_BAR; PG8_SCHED;
.LBB0_159:
	s_ashr_i32 s21, s20, 31
	s_lshl_b64 s[22:23], s[20:21], 21
	s_add_u32 s22, s33, s22
	s_addc_u32 s23, s54, s23
	s_ashr_i32 s19, s18, 31
	s_lshl_b64 s[24:25], s[18:19], 21
	s_add_u32 s24, s36, s24
	v_mov_b32_e32 v127, 0
	s_addc_u32 s25, s37, s25
	s_and_b64 vcc, exec, s[6:7]
	v_mov_b32_e32 v126, v127
	v_mov_b32_e32 v125, v127
	v_mov_b32_e32 v124, v127
	v_mov_b32_e32 v123, v127
	v_mov_b32_e32 v122, v127
	v_mov_b32_e32 v121, v127
	v_mov_b32_e32 v120, v127
	v_mov_b32_e32 v111, v127
	v_mov_b32_e32 v110, v127
	v_mov_b32_e32 v109, v127
	v_mov_b32_e32 v108, v127
	v_mov_b32_e32 v107, v127
	v_mov_b32_e32 v106, v127
	v_mov_b32_e32 v105, v127
	v_mov_b32_e32 v104, v127
	v_mov_b32_e32 v95, v127
	v_mov_b32_e32 v94, v127
	v_mov_b32_e32 v93, v127
	v_mov_b32_e32 v92, v127
	v_mov_b32_e32 v91, v127
	v_mov_b32_e32 v90, v127
	v_mov_b32_e32 v89, v127
	v_mov_b32_e32 v88, v127
	v_mov_b32_e32 v79, v127
	v_mov_b32_e32 v78, v127
	v_mov_b32_e32 v77, v127
	v_mov_b32_e32 v76, v127
	v_mov_b32_e32 v75, v127
	v_mov_b32_e32 v74, v127
	v_mov_b32_e32 v73, v127
	v_mov_b32_e32 v72, v127
	v_mov_b32_e32 v119, v127
	v_mov_b32_e32 v118, v127
	v_mov_b32_e32 v117, v127
	v_mov_b32_e32 v116, v127
	v_mov_b32_e32 v115, v127
	v_mov_b32_e32 v114, v127
	v_mov_b32_e32 v113, v127
	v_mov_b32_e32 v112, v127
	v_mov_b32_e32 v103, v127
	v_mov_b32_e32 v102, v127
	v_mov_b32_e32 v101, v127
	v_mov_b32_e32 v100, v127
	v_mov_b32_e32 v99, v127
	v_mov_b32_e32 v98, v127
	v_mov_b32_e32 v97, v127
	v_mov_b32_e32 v96, v127
	v_mov_b32_e32 v87, v127
	v_mov_b32_e32 v86, v127
	v_mov_b32_e32 v85, v127
	v_mov_b32_e32 v84, v127
	v_mov_b32_e32 v83, v127
	v_mov_b32_e32 v82, v127
	v_mov_b32_e32 v81, v127
	v_mov_b32_e32 v80, v127
	v_mov_b32_e32 v71, v127
	v_mov_b32_e32 v70, v127
	v_mov_b32_e32 v69, v127
	v_mov_b32_e32 v68, v127
	v_mov_b32_e32 v67, v127
	v_mov_b32_e32 v66, v127
	v_mov_b32_e32 v65, v127
	v_mov_b32_e32 v64, v127
	v_mov_b32_e32 v63, v127
	v_mov_b32_e32 v62, v127
	v_mov_b32_e32 v61, v127
	v_mov_b32_e32 v60, v127
	v_mov_b32_e32 v59, v127
	v_mov_b32_e32 v58, v127
	v_mov_b32_e32 v57, v127
	v_mov_b32_e32 v56, v127
	v_mov_b32_e32 v47, v127
	v_mov_b32_e32 v46, v127
	v_mov_b32_e32 v45, v127
	v_mov_b32_e32 v44, v127
	v_mov_b32_e32 v43, v127
	v_mov_b32_e32 v42, v127
	v_mov_b32_e32 v41, v127
	v_mov_b32_e32 v40, v127
	v_mov_b32_e32 v31, v127
	v_mov_b32_e32 v30, v127
	v_mov_b32_e32 v29, v127
	v_mov_b32_e32 v28, v127
	v_mov_b32_e32 v27, v127
	v_mov_b32_e32 v26, v127
	v_mov_b32_e32 v25, v127
	v_mov_b32_e32 v24, v127
	v_mov_b32_e32 v15, v127
	v_mov_b32_e32 v14, v127
	v_mov_b32_e32 v13, v127
	v_mov_b32_e32 v12, v127
	v_mov_b32_e32 v11, v127
	v_mov_b32_e32 v10, v127
	v_mov_b32_e32 v9, v127
	v_mov_b32_e32 v8, v127
	v_mov_b32_e32 v55, v127
	v_mov_b32_e32 v54, v127
	v_mov_b32_e32 v53, v127
	v_mov_b32_e32 v52, v127
	v_mov_b32_e32 v51, v127
	v_mov_b32_e32 v50, v127
	v_mov_b32_e32 v49, v127
	v_mov_b32_e32 v48, v127
	v_mov_b32_e32 v39, v127
	v_mov_b32_e32 v38, v127
	v_mov_b32_e32 v37, v127
	v_mov_b32_e32 v36, v127
	v_mov_b32_e32 v35, v127
	v_mov_b32_e32 v34, v127
	v_mov_b32_e32 v33, v127
	v_mov_b32_e32 v32, v127
	v_mov_b32_e32 v23, v127
	v_mov_b32_e32 v22, v127
	v_mov_b32_e32 v21, v127
	v_mov_b32_e32 v20, v127
	v_mov_b32_e32 v19, v127
	v_mov_b32_e32 v18, v127
	v_mov_b32_e32 v17, v127
	v_mov_b32_e32 v16, v127
	v_mov_b32_e32 v7, v127
	v_mov_b32_e32 v6, v127
	v_mov_b32_e32 v5, v127
	v_mov_b32_e32 v4, v127
	v_mov_b32_e32 v3, v127
	v_mov_b32_e32 v2, v127
	s_waitcnt lgkmcnt(0)
	v_mov_b32_e32 v1, v127
	v_mov_b32_e32 v0, v127
	s_cbranch_vccnz .LBB0_162
	s_and_b64 s[38:39], s[8:9], exec
	s_cselect_b32 s19, s23, s31
	s_cselect_b32 s21, s22, s30
	s_cselect_b32 s27, s25, s35
	s_cselect_b32 s29, s24, s34
	s_add_u32 s30, s30, 0x100080
	s_addc_u32 s31, s31, 0
	s_add_u32 s62, s34, 0x100
	v_mov_b32_e32 v0, 0
	s_addc_u32 s63, s35, 0
	s_mov_b32 s34, 0
	v_mov_b32_e32 v1, v0
.LBB0_161:
	ds_read_b128 v[154:157], v150
	ds_read_b128 v[158:161], v150 offset:1024
	ds_read_b128 v[162:165], v150 offset:2048
	ds_read_b128 v[166:169], v150 offset:3072
	ds_read_b128 v[170:173], v151
	ds_read_b128 v[174:177], v151 offset:1024
	ds_read_b128 v[182:185], v151 offset:2048
	ds_read_b128 v[186:189], v151 offset:3072
	s_add_i32 s64, s34, 2
	s_add_u32 s35, s30, 0xfff00080
	s_addc_u32 s38, s31, -1
	s_cmp_eq_u32 s53, s34
	s_cselect_b32 s34, s29, s62
	s_cselect_b32 s39, s19, s38
	s_cselect_b32 s38, s21, s35
	s_cselect_b32 s35, s27, s63
	v_lshl_add_u64 v[146:147], s[30:31], 0, v[138:139]
	s_add_i32 m0, s41, 0xc000
	ds_read_b128 v[190:193], v152
	ds_read_b128 v[194:197], v152 offset:1024
	ds_read_b128 v[198:201], v152 offset:2048
	ds_read_b128 v[202:205], v152 offset:3072
	ds_read_b128 v[206:209], v152 offset:4096
	ds_read_b128 v[210:213], v152 offset:5120
	ds_read_b128 v[214:217], v152 offset:6144
	ds_read_b128 v[218:221], v152 offset:7168
	global_load_lds_dwordx4 v[146:147], off
	v_lshl_add_u64 v[146:147], s[30:31], 0, v[140:141]
	s_add_i32 m0, s41, 0xe000
	s_nop 0
	global_load_lds_dwordx4 v[146:147], off
	s_waitcnt vmcnt(8)
	s_waitcnt lgkmcnt(0)
	s_setprio 1
	s_barrier
; #define PG8_STAGE(bufoff, gbase, voff) do { _Pragma("unroll") for (int _i = 0; _i < 2; ++_i) \
;         __builtin_amdgcn_global_load_lds((const unsigned*)((const char*)(gbase) + (voff)[_i]), (LAS unsigned*)(lds + (bufoff) + ldsw + _i * 8192), 16, 0, 0); } while (0)
; #define PG8_LDA(dst, b, h) do { _Pragma("unroll") for (int m = 0; m < 4; ++m) _Pragma("unroll") for (int k = 0; k < 2; ++k) dst[m][k] = *(const LAS bf16x8*)(lds + PG8_SA(b, h) + aoff + m * 2048 + k * 1024); } while (0)
; #define PG8_MMA(ai, bj, At, Bt) do { __builtin_amdgcn_s_setprio(1); _Pragma("unroll") for (int m = 0; m < 4; ++m) _Pragma("unroll") for (int n = 0; n < 2; ++n) _Pragma("unroll") for (int k = 0; k < 2; ++k) \
;         acc[ai][bj][m][n] = __builtin_amdgcn_mfma_f32_16x16x32_bf16(Bt[n][k], At[m][k], acc[ai][bj][m][n], 0, 0, 0); __builtin_amdgcn_s_setprio(0); } while (0)
; #define PG8_WAIT_V(n) asm volatile("s_waitcnt vmcnt(" #n ")" ::: "memory")
; #define PG8_WAIT_L(n) asm volatile("s_waitcnt lgkmcnt(" #n ")" ::: "memory")
; #define PG8_BAR __builtin_amdgcn_s_barrier()
; #define PG8_SCHED __builtin_amdgcn_sched_barrier(0)
; template <class Epi>
; DI void gemm_phase(LAS unsigned char* lds, const Gemm g, const StaticOrder& S, const Epi& E) {
;     ...
;             PG8_WAIT_V(8); PG8_WAIT_L(0); PG8_BAR; PG8_MMA(0, 0, At, B0); PG8_MMA(0, 1, At, B1); PG8_BAR; PG8_SCHED;
;             PG8_LDA(At, 0, 1); PG8_STAGE(PG8_SB(0, 0), b2, voffB); PG8_STAGE(PG8_SB(0, 1), b2 + hstepB, voffB); PG8_STAGE(PG8_SA(0, 0), a2, voffA);
;             PG8_WAIT_V(8); PG8_WAIT_L(0); PG8_BAR; PG8_MMA(1, 0, At, B0); PG8_MMA(1, 1, At, B1); PG8_BAR; PG8_SCHED;
	v_mfma_f32_16x16x32_bf16 v[124:127], v[154:157], v[190:193], v[124:127]
	v_mfma_f32_16x16x32_bf16 v[124:127], v[158:161], v[194:197], v[124:127]
	v_mfma_f32_16x16x32_bf16 v[120:123], v[162:165], v[190:193], v[120:123]
	v_mfma_f32_16x16x32_bf16 v[120:123], v[166:169], v[194:197], v[120:123]
	v_mfma_f32_16x16x32_bf16 v[108:111], v[154:157], v[198:201], v[108:111]
	v_mfma_f32_16x16x32_bf16 v[108:111], v[158:161], v[202:205], v[108:111]
	v_mfma_f32_16x16x32_bf16 v[104:107], v[162:165], v[198:201], v[104:107]
	v_mfma_f32_16x16x32_bf16 v[104:107], v[166:169], v[202:205], v[104:107]
	v_mfma_f32_16x16x32_bf16 v[92:95], v[154:157], v[206:209], v[92:95]
	v_mfma_f32_16x16x32_bf16 v[92:95], v[158:161], v[210:213], v[92:95]
	v_mfma_f32_16x16x32_bf16 v[88:91], v[162:165], v[206:209], v[88:91]
	v_mfma_f32_16x16x32_bf16 v[88:91], v[166:169], v[210:213], v[88:91]
	v_mfma_f32_16x16x32_bf16 v[76:79], v[154:157], v[214:217], v[76:79]
	v_mfma_f32_16x16x32_bf16 v[76:79], v[158:161], v[218:221], v[76:79]
	v_mfma_f32_16x16x32_bf16 v[72:75], v[162:165], v[214:217], v[72:75]
	v_mfma_f32_16x16x32_bf16 v[72:75], v[166:169], v[218:221], v[72:75]
	s_setprio 0
	s_setprio 1
	v_mfma_f32_16x16x32_bf16 v[116:119], v[170:173], v[190:193], v[116:119]
	v_mfma_f32_16x16x32_bf16 v[116:119], v[174:177], v[194:197], v[116:119]
	v_mfma_f32_16x16x32_bf16 v[112:115], v[182:185], v[190:193], v[112:115]
	v_mfma_f32_16x16x32_bf16 v[112:115], v[186:189], v[194:197], v[112:115]
	v_mfma_f32_16x16x32_bf16 v[100:103], v[170:173], v[198:201], v[100:103]
	v_mfma_f32_16x16x32_bf16 v[100:103], v[174:177], v[202:205], v[100:103]
	v_mfma_f32_16x16x32_bf16 v[96:99], v[182:185], v[198:201], v[96:99]
	v_mfma_f32_16x16x32_bf16 v[96:99], v[186:189], v[202:205], v[96:99]
	v_mfma_f32_16x16x32_bf16 v[84:87], v[170:173], v[206:209], v[84:87]
	v_mfma_f32_16x16x32_bf16 v[84:87], v[174:177], v[210:213], v[84:87]
	v_mfma_f32_16x16x32_bf16 v[80:83], v[182:185], v[206:209], v[80:83]
	v_mfma_f32_16x16x32_bf16 v[80:83], v[186:189], v[210:213], v[80:83]
	v_mfma_f32_16x16x32_bf16 v[68:71], v[170:173], v[214:217], v[68:71]
	v_mfma_f32_16x16x32_bf16 v[68:71], v[174:177], v[218:221], v[68:71]
	v_mfma_f32_16x16x32_bf16 v[64:67], v[182:185], v[214:217], v[64:67]
	v_mfma_f32_16x16x32_bf16 v[64:67], v[186:189], v[218:221], v[64:67]
	s_setprio 0
	s_barrier
	s_add_i32 s65, s58, s40
	v_lshl_add_u64 v[146:147], s[34:35], 0, v[130:131]
	s_mov_b32 m0, s65
	ds_read_b128 v[190:193], v152 offset:16384
	ds_read_b128 v[194:197], v152 offset:17408
	ds_read_b128 v[198:201], v152 offset:18432
	ds_read_b128 v[202:205], v152 offset:19456
	ds_read_b128 v[206:209], v152 offset:20480
	ds_read_b128 v[210:213], v152 offset:21504
	ds_read_b128 v[214:217], v152 offset:22528
	ds_read_b128 v[218:221], v152 offset:23552
	global_load_lds_dwordx4 v[146:147], off
	s_add_i32 m0, s65, 0x2000
	s_add_u32 s66, s34, 0x100000
	v_lshl_add_u64 v[178:179], s[34:35], 0, v[134:135]
	s_addc_u32 s67, s35, 0
	s_add_i32 s65, s59, s40
	global_load_lds_dwordx4 v[178:179], off
	v_lshl_add_u64 v[222:223], s[66:67], 0, v[130:131]
	s_mov_b32 m0, s65
	v_lshl_add_u64 v[224:225], s[38:39], 0, v[132:133]
	global_load_lds_dwordx4 v[222:223], off
	v_lshl_add_u64 v[222:223], s[66:67], 0, v[134:135]
	s_add_i32 m0, s65, 0x2000
	s_nop 0
	global_load_lds_dwordx4 v[222:223], off
	v_lshl_add_u64 v[222:223], s[38:39], 0, v[128:129]
	s_mov_b32 m0, s41
	s_nop 0
	global_load_lds_dwordx4 v[222:223], off
	s_mov_b32 m0, s42
	s_nop 0
	global_load_lds_dwordx4 v[224:225], off
	s_waitcnt vmcnt(8)
	s_waitcnt lgkmcnt(0)
	s_setprio 1
	s_barrier
	v_mfma_f32_16x16x32_bf16 v[60:63], v[154:157], v[190:193], v[60:63]
	v_mfma_f32_16x16x32_bf16 v[60:63], v[158:161], v[194:197], v[60:63]
	v_mfma_f32_16x16x32_bf16 v[56:59], v[162:165], v[190:193], v[56:59]
	v_mfma_f32_16x16x32_bf16 v[56:59], v[166:169], v[194:197], v[56:59]
	v_mfma_f32_16x16x32_bf16 v[44:47], v[154:157], v[198:201], v[44:47]
	v_mfma_f32_16x16x32_bf16 v[44:47], v[158:161], v[202:205], v[44:47]
	v_mfma_f32_16x16x32_bf16 v[40:43], v[162:165], v[198:201], v[40:43]
	v_mfma_f32_16x16x32_bf16 v[40:43], v[166:169], v[202:205], v[40:43]
	v_mfma_f32_16x16x32_bf16 v[28:31], v[154:157], v[206:209], v[28:31]
	v_mfma_f32_16x16x32_bf16 v[28:31], v[158:161], v[210:213], v[28:31]
	v_mfma_f32_16x16x32_bf16 v[24:27], v[162:165], v[206:209], v[24:27]
	v_mfma_f32_16x16x32_bf16 v[24:27], v[166:169], v[210:213], v[24:27]
	v_mfma_f32_16x16x32_bf16 v[12:15], v[154:157], v[214:217], v[12:15]
	v_mfma_f32_16x16x32_bf16 v[12:15], v[158:161], v[218:221], v[12:15]
	v_mfma_f32_16x16x32_bf16 v[8:11], v[162:165], v[214:217], v[8:11]
	v_mfma_f32_16x16x32_bf16 v[8:11], v[166:169], v[218:221], v[8:11]
	s_setprio 0
	s_setprio 1
	v_mfma_f32_16x16x32_bf16 v[52:55], v[170:173], v[190:193], v[52:55]
	v_mfma_f32_16x16x32_bf16 v[52:55], v[174:177], v[194:197], v[52:55]
	v_mfma_f32_16x16x32_bf16 v[48:51], v[182:185], v[190:193], v[48:51]
	v_mfma_f32_16x16x32_bf16 v[48:51], v[186:189], v[194:197], v[48:51]
	v_mfma_f32_16x16x32_bf16 v[36:39], v[170:173], v[198:201], v[36:39]
	v_mfma_f32_16x16x32_bf16 v[36:39], v[174:177], v[202:205], v[36:39]
	v_mfma_f32_16x16x32_bf16 v[32:35], v[182:185], v[198:201], v[32:35]
	v_mfma_f32_16x16x32_bf16 v[32:35], v[186:189], v[202:205], v[32:35]
	v_mfma_f32_16x16x32_bf16 v[20:23], v[170:173], v[206:209], v[20:23]
	v_mfma_f32_16x16x32_bf16 v[20:23], v[174:177], v[210:213], v[20:23]
	v_mfma_f32_16x16x32_bf16 v[16:19], v[182:185], v[206:209], v[16:19]
	v_mfma_f32_16x16x32_bf16 v[16:19], v[186:189], v[210:213], v[16:19]
	v_mfma_f32_16x16x32_bf16 v[4:7], v[170:173], v[214:217], v[4:7]
	v_mfma_f32_16x16x32_bf16 v[4:7], v[174:177], v[218:221], v[4:7]
	v_mfma_f32_16x16x32_bf16 v[0:3], v[182:185], v[214:217], v[0:3]
	v_mfma_f32_16x16x32_bf16 v[0:3], v[186:189], v[218:221], v[0:3]
	s_setprio 0
	s_barrier
; #define PG8_STAGE(bufoff, gbase, voff) do { _Pragma("unroll") for (int _i = 0; _i < 2; ++_i) \
;         __builtin_amdgcn_global_load_lds((const unsigned*)((const char*)(gbase) + (voff)[_i]), (LAS unsigned*)(lds + (bufoff) + ldsw + _i * 8192), 16, 0, 0); } while (0)
; #define PG8_LDA(dst, b, h) do { _Pragma("unroll") for (int m = 0; m < 4; ++m) _Pragma("unroll") for (int k = 0; k < 2; ++k) dst[m][k] = *(const LAS bf16x8*)(lds + PG8_SA(b, h) + aoff + m * 2048 + k * 1024); } while (0)
; #define PG8_LDB(dst, b, h) do { _Pragma("unroll") for (int n = 0; n < 2; ++n) _Pragma("unroll") for (int k = 0; k < 2; ++k) dst[n][k] = *(const LAS bf16x8*)(lds + PG8_SB(b, h) + boff + n * 2048 + k * 1024); } while (0)
; #define PG8_MMA(ai, bj, At, Bt) do { __builtin_amdgcn_s_setprio(1); _Pragma("unroll") for (int m = 0; m < 4; ++m) _Pragma("unroll") for (int n = 0; n < 2; ++n) _Pragma("unroll") for (int k = 0; k < 2; ++k) \
;         acc[ai][bj][m][n] = __builtin_amdgcn_mfma_f32_16x16x32_bf16(Bt[n][k], At[m][k], acc[ai][bj][m][n], 0, 0, 0); __builtin_amdgcn_s_setprio(0); } while (0)
; #define PG8_WAIT_V(n) asm volatile("s_waitcnt vmcnt(" #n ")" ::: "memory")
; #define PG8_WAIT_L(n) asm volatile("s_waitcnt lgkmcnt(" #n ")" ::: "memory")
; #define PG8_BAR __builtin_amdgcn_s_barrier()
; #define PG8_SCHED __builtin_amdgcn_sched_barrier(0)
; template <class Epi>
; DI void gemm_phase(LAS unsigned char* lds, const Gemm g, const StaticOrder& S, const Epi& E) {
;     ...
;             PG8_LDB(B0, 1, 0); PG8_LDB(B1, 1, 1); PG8_SCHED; PG8_LDA(At, 1, 0); PG8_STAGE(PG8_SA(0, 1), a2 + hstepA, voffA);
;             PG8_WAIT_V(8); PG8_WAIT_L(0); PG8_BAR; PG8_MMA(0, 0, At, B0); PG8_MMA(0, 1, At, B1); PG8_BAR; PG8_SCHED;
	s_add_i32 s65, 0, 0x18000
	s_add_i32 s66, 0, 0x1c000
	v_add_u32_e32 v166, s65, v149
	v_add_u32_e32 v181, s66, v149
	ds_read_b128 v[154:157], v166
	ds_read_b128 v[158:161], v166 offset:1024
	ds_read_b128 v[162:165], v166 offset:2048
	ds_read_b128 v[166:169], v166 offset:3072
	ds_read_b128 v[170:173], v181
	ds_read_b128 v[174:177], v181 offset:1024
	ds_read_b128 v[182:185], v181 offset:2048
	ds_read_b128 v[186:189], v181 offset:3072
	s_add_u32 s38, s38, 0x100000
	s_addc_u32 s39, s39, 0
	s_mov_b32 m0, s43
	v_lshl_add_u64 v[226:227], s[38:39], 0, v[128:129]
	ds_read_b128 v[190:193], v152 offset:32768
	ds_read_b128 v[194:197], v152 offset:33792
	ds_read_b128 v[198:201], v152 offset:34816
	ds_read_b128 v[202:205], v152 offset:35840
	ds_read_b128 v[206:209], v152 offset:36864
	ds_read_b128 v[210:213], v152 offset:37888
	ds_read_b128 v[214:217], v152 offset:38912
	ds_read_b128 v[218:221], v152 offset:39936
	global_load_lds_dwordx4 v[226:227], off
	v_lshl_add_u64 v[226:227], s[38:39], 0, v[132:133]
	s_mov_b32 m0, s46
	s_nop 0
	global_load_lds_dwordx4 v[226:227], off
	s_waitcnt vmcnt(8)
	s_waitcnt lgkmcnt(0)
	s_setprio 1
	s_barrier
	v_mfma_f32_16x16x32_bf16 v[124:127], v[154:157], v[190:193], v[124:127]
	v_mfma_f32_16x16x32_bf16 v[124:127], v[158:161], v[194:197], v[124:127]
	v_mfma_f32_16x16x32_bf16 v[120:123], v[162:165], v[190:193], v[120:123]
	v_mfma_f32_16x16x32_bf16 v[120:123], v[166:169], v[194:197], v[120:123]
	v_mfma_f32_16x16x32_bf16 v[108:111], v[154:157], v[198:201], v[108:111]
	v_mfma_f32_16x16x32_bf16 v[108:111], v[158:161], v[202:205], v[108:111]
	v_mfma_f32_16x16x32_bf16 v[104:107], v[162:165], v[198:201], v[104:107]
	v_mfma_f32_16x16x32_bf16 v[104:107], v[166:169], v[202:205], v[104:107]
	v_mfma_f32_16x16x32_bf16 v[92:95], v[154:157], v[206:209], v[92:95]
	v_mfma_f32_16x16x32_bf16 v[92:95], v[158:161], v[210:213], v[92:95]
	v_mfma_f32_16x16x32_bf16 v[88:91], v[162:165], v[206:209], v[88:91]
	v_mfma_f32_16x16x32_bf16 v[88:91], v[166:169], v[210:213], v[88:91]
	v_mfma_f32_16x16x32_bf16 v[76:79], v[154:157], v[214:217], v[76:79]
	v_mfma_f32_16x16x32_bf16 v[76:79], v[158:161], v[218:221], v[76:79]
	v_mfma_f32_16x16x32_bf16 v[72:75], v[162:165], v[214:217], v[72:75]
	v_mfma_f32_16x16x32_bf16 v[72:75], v[166:169], v[218:221], v[72:75]
	s_setprio 0
	s_setprio 1
	v_mfma_f32_16x16x32_bf16 v[116:119], v[170:173], v[190:193], v[116:119]
	v_mfma_f32_16x16x32_bf16 v[116:119], v[174:177], v[194:197], v[116:119]
	v_mfma_f32_16x16x32_bf16 v[112:115], v[182:185], v[190:193], v[112:115]
	v_mfma_f32_16x16x32_bf16 v[112:115], v[186:189], v[194:197], v[112:115]
	v_mfma_f32_16x16x32_bf16 v[100:103], v[170:173], v[198:201], v[100:103]
	v_mfma_f32_16x16x32_bf16 v[100:103], v[174:177], v[202:205], v[100:103]
	v_mfma_f32_16x16x32_bf16 v[96:99], v[182:185], v[198:201], v[96:99]
	v_mfma_f32_16x16x32_bf16 v[96:99], v[186:189], v[202:205], v[96:99]
	v_mfma_f32_16x16x32_bf16 v[84:87], v[170:173], v[206:209], v[84:87]
	v_mfma_f32_16x16x32_bf16 v[84:87], v[174:177], v[210:213], v[84:87]
	v_mfma_f32_16x16x32_bf16 v[80:83], v[182:185], v[206:209], v[80:83]
	v_mfma_f32_16x16x32_bf16 v[80:83], v[186:189], v[210:213], v[80:83]
	v_mfma_f32_16x16x32_bf16 v[68:71], v[170:173], v[214:217], v[68:71]
	v_mfma_f32_16x16x32_bf16 v[68:71], v[174:177], v[218:221], v[68:71]
	v_mfma_f32_16x16x32_bf16 v[64:67], v[182:185], v[214:217], v[64:67]
	v_mfma_f32_16x16x32_bf16 v[64:67], v[186:189], v[218:221], v[64:67]
	s_setprio 0
	s_barrier
; #define PG8_STAGE(bufoff, gbase, voff) do { _Pragma("unroll") for (int _i = 0; _i < 2; ++_i) \
;         __builtin_amdgcn_global_load_lds((const unsigned*)((const char*)(gbase) + (voff)[_i]), (LAS unsigned*)(lds + (bufoff) + ldsw + _i * 8192), 16, 0, 0); } while (0)
; #define PG8_LDA(dst, b, h) do { _Pragma("unroll") for (int m = 0; m < 4; ++m) _Pragma("unroll") for (int k = 0; k < 2; ++k) dst[m][k] = *(const LAS bf16x8*)(lds + PG8_SA(b, h) + aoff + m * 2048 + k * 1024); } while (0)
; #define PG8_MMA(ai, bj, At, Bt) do { __builtin_amdgcn_s_setprio(1); _Pragma("unroll") for (int m = 0; m < 4; ++m) _Pragma("unroll") for (int n = 0; n < 2; ++n) _Pragma("unroll") for (int k = 0; k < 2; ++k) \
;         acc[ai][bj][m][n] = __builtin_amdgcn_mfma_f32_16x16x32_bf16(Bt[n][k], At[m][k], acc[ai][bj][m][n], 0, 0, 0); __builtin_amdgcn_s_setprio(0); } while (0)
; #define PG8_WAIT_V(n) asm volatile("s_waitcnt vmcnt(" #n ")" ::: "memory")
; #define PG8_WAIT_L(n) asm volatile("s_waitcnt lgkmcnt(" #n ")" ::: "memory")
; #define PG8_BAR __builtin_amdgcn_s_barrier()
; #define PG8_SCHED __builtin_amdgcn_sched_barrier(0)
; template <class Epi>
; DI void gemm_phase(LAS unsigned char* lds, const Gemm g, const StaticOrder& S, const Epi& E) {
;     ...
;             PG8_LDA(At, 1, 1); PG8_STAGE(PG8_SB(1, 0), b3, voffB); PG8_STAGE(PG8_SB(1, 1), b3 + hstepB, voffB); PG8_STAGE(PG8_SA(1, 0), a3, voffA);
;             PG8_WAIT_V(8); PG8_WAIT_L(0); PG8_BAR; PG8_MMA(1, 0, At, B0); PG8_MMA(1, 1, At, B1); PG8_BAR; PG8_SCHED;
;         }
	s_add_i32 s38, s65, s40
	v_lshl_add_u64 v[146:147], v[146:147], 0, s[14:15]
	s_mov_b32 m0, s38
	ds_read_b128 v[190:193], v152 offset:49152
	ds_read_b128 v[194:197], v152 offset:50176
	ds_read_b128 v[198:201], v152 offset:51200
	ds_read_b128 v[202:205], v152 offset:52224
	ds_read_b128 v[206:209], v152 offset:53248
	ds_read_b128 v[210:213], v152 offset:54272
	ds_read_b128 v[214:217], v152 offset:55296
	ds_read_b128 v[218:221], v152 offset:56320
	global_load_lds_dwordx4 v[146:147], off
	s_add_i32 m0, s38, 0x2000
	s_add_u32 s34, s34, 0x100080
	v_lshl_add_u64 v[146:147], v[178:179], 0, s[14:15]
	s_addc_u32 s35, s35, 0
	s_add_i32 s38, s66, s40
	global_load_lds_dwordx4 v[146:147], off
	v_lshl_add_u64 v[146:147], s[34:35], 0, v[130:131]
	s_mov_b32 m0, s38
	s_nop 0
	global_load_lds_dwordx4 v[146:147], off
	v_lshl_add_u64 v[146:147], s[34:35], 0, v[134:135]
	s_add_i32 m0, s38, 0x2000
	s_nop 0
	global_load_lds_dwordx4 v[146:147], off
	v_lshl_add_u64 v[146:147], v[222:223], 0, s[14:15]
	s_mov_b32 m0, s51
	s_nop 0
	global_load_lds_dwordx4 v[146:147], off
	v_lshl_add_u64 v[146:147], v[224:225], 0, s[14:15]
	s_mov_b32 m0, s52
	s_nop 0
	global_load_lds_dwordx4 v[146:147], off
	s_waitcnt vmcnt(8)
	s_waitcnt lgkmcnt(0)
	s_setprio 1
	s_barrier
	v_mfma_f32_16x16x32_bf16 v[60:63], v[154:157], v[190:193], v[60:63]
	v_mfma_f32_16x16x32_bf16 v[60:63], v[158:161], v[194:197], v[60:63]
	v_mfma_f32_16x16x32_bf16 v[56:59], v[162:165], v[190:193], v[56:59]
	v_mfma_f32_16x16x32_bf16 v[56:59], v[166:169], v[194:197], v[56:59]
	v_mfma_f32_16x16x32_bf16 v[44:47], v[154:157], v[198:201], v[44:47]
	v_mfma_f32_16x16x32_bf16 v[44:47], v[158:161], v[202:205], v[44:47]
	v_mfma_f32_16x16x32_bf16 v[40:43], v[162:165], v[198:201], v[40:43]
	v_mfma_f32_16x16x32_bf16 v[40:43], v[166:169], v[202:205], v[40:43]
	v_mfma_f32_16x16x32_bf16 v[28:31], v[154:157], v[206:209], v[28:31]
	v_mfma_f32_16x16x32_bf16 v[28:31], v[158:161], v[210:213], v[28:31]
	v_mfma_f32_16x16x32_bf16 v[24:27], v[162:165], v[206:209], v[24:27]
	v_mfma_f32_16x16x32_bf16 v[24:27], v[166:169], v[210:213], v[24:27]
	v_mfma_f32_16x16x32_bf16 v[12:15], v[154:157], v[214:217], v[12:15]
	v_mfma_f32_16x16x32_bf16 v[12:15], v[158:161], v[218:221], v[12:15]
	v_mfma_f32_16x16x32_bf16 v[8:11], v[162:165], v[214:217], v[8:11]
	v_mfma_f32_16x16x32_bf16 v[8:11], v[166:169], v[218:221], v[8:11]
	s_setprio 0
	s_setprio 1
	v_mfma_f32_16x16x32_bf16 v[52:55], v[170:173], v[190:193], v[52:55]
	v_mfma_f32_16x16x32_bf16 v[52:55], v[174:177], v[194:197], v[52:55]
	v_mfma_f32_16x16x32_bf16 v[48:51], v[182:185], v[190:193], v[48:51]
	v_mfma_f32_16x16x32_bf16 v[48:51], v[186:189], v[194:197], v[48:51]
	v_mfma_f32_16x16x32_bf16 v[36:39], v[170:173], v[198:201], v[36:39]
	v_mfma_f32_16x16x32_bf16 v[36:39], v[174:177], v[202:205], v[36:39]
	v_mfma_f32_16x16x32_bf16 v[32:35], v[182:185], v[198:201], v[32:35]
	v_mfma_f32_16x16x32_bf16 v[32:35], v[186:189], v[202:205], v[32:35]
	v_mfma_f32_16x16x32_bf16 v[20:23], v[170:173], v[206:209], v[20:23]
	v_mfma_f32_16x16x32_bf16 v[20:23], v[174:177], v[210:213], v[20:23]
	v_mfma_f32_16x16x32_bf16 v[16:19], v[182:185], v[206:209], v[16:19]
	v_mfma_f32_16x16x32_bf16 v[16:19], v[186:189], v[210:213], v[16:19]
	v_mfma_f32_16x16x32_bf16 v[4:7], v[170:173], v[214:217], v[4:7]
	v_mfma_f32_16x16x32_bf16 v[4:7], v[174:177], v[218:221], v[4:7]
	v_mfma_f32_16x16x32_bf16 v[0:3], v[182:185], v[214:217], v[0:3]
	v_mfma_f32_16x16x32_bf16 v[0:3], v[186:189], v[218:221], v[0:3]
	s_setprio 0
	s_barrier
	s_add_u32 s30, s30, 0x100
	s_addc_u32 s31, s31, 0
	s_add_u32 s62, s62, 0x100
	s_addc_u32 s63, s63, 0
	s_cmp_ge_i32 s64, s50
	s_mov_b32 s34, s64
	s_cbranch_scc0 .LBB0_161

; template <class Epi>
; DI void gemm_phase(LAS unsigned char* lds, const Gemm g, const StaticOrder& S, const Epi& E) {
;     ...
;     f32x4 acc[2][2][4][2];
; #pragma unroll
;     for (int a = 0; a < 2; ++a)
; #pragma unroll
;         for (int b = 0; b < 2; ++b)
; #pragma unroll
;             for (int m = 0; m < 4; ++m)
; #pragma unroll
;                 for (int n = 0; n < 2; ++n) acc[a][b][m][n] = (f32x4){0.f, 0.f, 0.f, 0.f};
;     ...
;     for (;;) {
;         const bool has_next = S.next(ui + 1, nxt);
;         const char* nA = has_next ? (const char*)g.A + (size_t)nxt.pm * tstepA + PG8_KOFF(nxt) : cA; const char* nB = has_next ? (const char*)g.Bt + (size_t)nxt.pn * tstepB + PG8_KOFF(nxt) : cB;
.LBB0_199:
	s_ashr_i32 s21, s20, 31
	s_lshl_b64 s[22:23], s[20:21], 21
	s_add_u32 s22, s4, s22
	s_addc_u32 s23, s5, s23
	s_ashr_i32 s19, s18, 31
	s_lshl_b64 s[24:25], s[18:19], 21
	s_add_u32 s24, s33, s24
	v_mov_b32_e32 v123, 0
	s_addc_u32 s25, s54, s25
	s_andn2_b64 vcc, exec, s[12:13]
	v_mov_b32_e32 v122, v123
	v_mov_b32_e32 v121, v123
	v_mov_b32_e32 v120, v123
	v_mov_b32_e32 v127, v123
	v_mov_b32_e32 v126, v123
	v_mov_b32_e32 v125, v123
	v_mov_b32_e32 v124, v123
	v_mov_b32_e32 v111, v123
	v_mov_b32_e32 v110, v123
	v_mov_b32_e32 v109, v123
	v_mov_b32_e32 v108, v123
	v_mov_b32_e32 v107, v123
	v_mov_b32_e32 v106, v123
	v_mov_b32_e32 v105, v123
	v_mov_b32_e32 v104, v123
	v_mov_b32_e32 v95, v123
	v_mov_b32_e32 v94, v123
	v_mov_b32_e32 v93, v123
	v_mov_b32_e32 v92, v123
	v_mov_b32_e32 v91, v123
	v_mov_b32_e32 v90, v123
	v_mov_b32_e32 v89, v123
	v_mov_b32_e32 v88, v123
	v_mov_b32_e32 v79, v123
	v_mov_b32_e32 v78, v123
	v_mov_b32_e32 v77, v123
	v_mov_b32_e32 v76, v123
	v_mov_b32_e32 v75, v123
	v_mov_b32_e32 v74, v123
	v_mov_b32_e32 v73, v123
	v_mov_b32_e32 v72, v123
	v_mov_b32_e32 v119, v123
	v_mov_b32_e32 v118, v123
	v_mov_b32_e32 v117, v123
	v_mov_b32_e32 v116, v123
	v_mov_b32_e32 v115, v123
	v_mov_b32_e32 v114, v123
	v_mov_b32_e32 v113, v123
	v_mov_b32_e32 v112, v123
	v_mov_b32_e32 v103, v123
	v_mov_b32_e32 v102, v123
	v_mov_b32_e32 v101, v123
	v_mov_b32_e32 v100, v123
	v_mov_b32_e32 v99, v123
	v_mov_b32_e32 v98, v123
	v_mov_b32_e32 v97, v123
	v_mov_b32_e32 v96, v123
	v_mov_b32_e32 v87, v123
	v_mov_b32_e32 v86, v123
	v_mov_b32_e32 v85, v123
	v_mov_b32_e32 v84, v123
	v_mov_b32_e32 v83, v123
	v_mov_b32_e32 v82, v123
	v_mov_b32_e32 v81, v123
	v_mov_b32_e32 v80, v123
	v_mov_b32_e32 v71, v123
	v_mov_b32_e32 v70, v123
	v_mov_b32_e32 v69, v123
	v_mov_b32_e32 v68, v123
	v_mov_b32_e32 v67, v123
	v_mov_b32_e32 v66, v123
	v_mov_b32_e32 v65, v123
	v_mov_b32_e32 v64, v123
	v_mov_b32_e32 v63, v123
	v_mov_b32_e32 v62, v123
	v_mov_b32_e32 v61, v123
	v_mov_b32_e32 v60, v123
	v_mov_b32_e32 v59, v123
	v_mov_b32_e32 v58, v123
	v_mov_b32_e32 v57, v123
	v_mov_b32_e32 v56, v123
	v_mov_b32_e32 v47, v123
	v_mov_b32_e32 v46, v123
	v_mov_b32_e32 v45, v123
	v_mov_b32_e32 v44, v123
	v_mov_b32_e32 v43, v123
	v_mov_b32_e32 v42, v123
	v_mov_b32_e32 v41, v123
	v_mov_b32_e32 v40, v123
	v_mov_b32_e32 v31, v123
	v_mov_b32_e32 v30, v123
	v_mov_b32_e32 v29, v123
	v_mov_b32_e32 v28, v123
	v_mov_b32_e32 v27, v123
	v_mov_b32_e32 v26, v123
	v_mov_b32_e32 v25, v123
	v_mov_b32_e32 v24, v123
	v_mov_b32_e32 v15, v123
	v_mov_b32_e32 v14, v123
	v_mov_b32_e32 v13, v123
	v_mov_b32_e32 v12, v123
	v_mov_b32_e32 v11, v123
	v_mov_b32_e32 v10, v123
	v_mov_b32_e32 v9, v123
	v_mov_b32_e32 v8, v123
	v_mov_b32_e32 v55, v123
	v_mov_b32_e32 v54, v123
	v_mov_b32_e32 v53, v123
	v_mov_b32_e32 v52, v123
	v_mov_b32_e32 v51, v123
	v_mov_b32_e32 v50, v123
	v_mov_b32_e32 v49, v123
	v_mov_b32_e32 v48, v123
	v_mov_b32_e32 v39, v123
	v_mov_b32_e32 v38, v123
	v_mov_b32_e32 v37, v123
	v_mov_b32_e32 v36, v123
	v_mov_b32_e32 v35, v123
	v_mov_b32_e32 v34, v123
	v_mov_b32_e32 v33, v123
	v_mov_b32_e32 v32, v123
	v_mov_b32_e32 v23, v123
	v_mov_b32_e32 v22, v123
	v_mov_b32_e32 v21, v123
	v_mov_b32_e32 v20, v123
	v_mov_b32_e32 v19, v123
	v_mov_b32_e32 v18, v123
	v_mov_b32_e32 v17, v123
	v_mov_b32_e32 v16, v123
	v_mov_b32_e32 v7, v123
	v_mov_b32_e32 v6, v123
	v_mov_b32_e32 v5, v123
	v_mov_b32_e32 v4, v123
	v_mov_b32_e32 v3, v123
	v_mov_b32_e32 v2, v123
	v_mov_b32_e32 v1, v123
	v_mov_b32_e32 v0, v123
	s_cbranch_vccnz .LBB0_202
	s_and_b64 s[30:31], s[16:17], exec
	s_cselect_b32 s19, s23, s27
	s_cselect_b32 s21, s22, s26
	s_cselect_b32 s61, s25, s29
	s_cselect_b32 s62, s24, s28
	s_add_u32 s26, s26, 0x100080
	s_addc_u32 s27, s27, 0
	s_add_u32 s63, s28, 0x100
	s_addc_u32 s64, s29, 0
	s_mov_b32 s28, 0

; template <class Epi>
; DI void gemm_phase(LAS unsigned char* lds, const Gemm g, const StaticOrder& S, const Epi& E) {
;     ...
;     f32x4 acc[2][2][4][2];
; #pragma unroll
;     for (int a = 0; a < 2; ++a)
; #pragma unroll
;         for (int b = 0; b < 2; ++b)
; #pragma unroll
;             for (int m = 0; m < 4; ++m)
; #pragma unroll
;                 for (int n = 0; n < 2; ++n) acc[a][b][m][n] = (f32x4){0.f, 0.f, 0.f, 0.f};
; __global__ void __launch_bounds__(512, 2) mk_fwd(Params prm) {
;     ...
;         { pg8::Gemm g{(const bf16_t*)(ws + WS_R0), (const bf16_t*)(ws + WS_WIN) + (size_t)4096 * D, T, 256, 1024, D, D}; pg8::StaticOrder So; So.init(T, 256, G, cid, 2);
;           EpiKr E{(float*)(ws + WS_KRP)};
;           pg8::gemm_phase<EpiKr>(lds, g, So, E); }
.LBB0_218:
	v_mov_b32_e32 v63, 0
	s_and_b64 vcc, exec, s[4:5]
	v_mov_b32_e32 v62, v63
	v_mov_b32_e32 v61, v63
	v_mov_b32_e32 v60, v63
	v_mov_b32_e32 v59, v63
	v_mov_b32_e32 v58, v63
	v_mov_b32_e32 v57, v63
	v_mov_b32_e32 v56, v63
	v_mov_b32_e32 v55, v63
	v_mov_b32_e32 v54, v63
	v_mov_b32_e32 v53, v63
	v_mov_b32_e32 v52, v63
	v_mov_b32_e32 v51, v63
	v_mov_b32_e32 v50, v63
	v_mov_b32_e32 v49, v63
	v_mov_b32_e32 v48, v63
	v_mov_b32_e32 v47, v63
	v_mov_b32_e32 v46, v63
	v_mov_b32_e32 v45, v63
	v_mov_b32_e32 v44, v63
	v_mov_b32_e32 v43, v63
	v_mov_b32_e32 v42, v63
	v_mov_b32_e32 v41, v63
	v_mov_b32_e32 v40, v63
	v_mov_b32_e32 v39, v63
	v_mov_b32_e32 v38, v63
	v_mov_b32_e32 v37, v63
	v_mov_b32_e32 v36, v63
	v_mov_b32_e32 v35, v63
	v_mov_b32_e32 v34, v63
	v_mov_b32_e32 v33, v63
	v_mov_b32_e32 v32, v63
	v_mov_b32_e32 v31, v63
	v_mov_b32_e32 v30, v63
	v_mov_b32_e32 v29, v63
	v_mov_b32_e32 v28, v63
	v_mov_b32_e32 v27, v63
	v_mov_b32_e32 v26, v63
	v_mov_b32_e32 v25, v63
	v_mov_b32_e32 v24, v63
	v_mov_b32_e32 v23, v63
	v_mov_b32_e32 v22, v63
	v_mov_b32_e32 v21, v63
	v_mov_b32_e32 v20, v63
	v_mov_b32_e32 v19, v63
	v_mov_b32_e32 v18, v63
	v_mov_b32_e32 v17, v63
	v_mov_b32_e32 v16, v63
	v_mov_b32_e32 v15, v63
	v_mov_b32_e32 v14, v63
	v_mov_b32_e32 v13, v63
	v_mov_b32_e32 v12, v63
	v_mov_b32_e32 v11, v63
	v_mov_b32_e32 v10, v63
	v_mov_b32_e32 v9, v63
	v_mov_b32_e32 v8, v63
	v_mov_b32_e32 v7, v63
	v_mov_b32_e32 v6, v63
	v_mov_b32_e32 v5, v63
	v_mov_b32_e32 v4, v63
	v_mov_b32_e32 v3, v63
	v_mov_b32_e32 v2, v63
	v_mov_b32_e32 v1, v63
	v_mov_b32_e32 v0, v63
	s_cbranch_vccnz .LBB0_221
	s_add_u32 s46, s46, 0x100080
	s_addc_u32 s47, s47, 0
	s_add_u32 s13, s50, 0x100
	s_addc_u32 s41, s51, 0
	s_mov_b32 s50, 0

; template <class Epi>
; DI void gemm_phase(LAS unsigned char* lds, const Gemm g, const StaticOrder& S, const Epi& E) {
;     ...
;     f32x4 acc[2][2][4][2];
; #pragma unroll
;     for (int a = 0; a < 2; ++a)
; #pragma unroll
;         for (int b = 0; b < 2; ++b)
; #pragma unroll
;             for (int m = 0; m < 4; ++m)
; #pragma unroll
;                 for (int n = 0; n < 2; ++n) acc[a][b][m][n] = (f32x4){0.f, 0.f, 0.f, 0.f};
; __global__ void __launch_bounds__(512, 2) mk_fwd(Params prm) {
;     ...
;         { pg8::Gemm g{(const bf16_t*)(ws + WS_PROJ) + PJ_CQ, (const bf16_t*)(ws + WS_WQUP), T, QW, 1024, DIN_P, 1024}; pg8::StaticOrder So; So.init(T, QW, G, cid);
;           EpiUp<0> E{ssq, 1.0f / 1024.0f, MLA_QSCALE, (bf16_t*)(ws + WS_Q), QW, cs, nullptr};
;           pg8::gemm_phase<EpiUp<0>>(lds, g, So, E); }
.LBB0_300:
	s_ashr_i32 s41, s40, 31
	s_lshl_b64 s[12:13], s[40:41], 19
	s_add_u32 s46, s57, s12
	v_mov_b32_e32 v123, 0
	s_addc_u32 s47, s58, s13
	s_andn2_b64 vcc, exec, s[34:35]
	v_mov_b32_e32 v122, v123
	v_mov_b32_e32 v121, v123
	v_mov_b32_e32 v120, v123
	v_mov_b32_e32 v127, v123
	v_mov_b32_e32 v126, v123
	v_mov_b32_e32 v125, v123
	v_mov_b32_e32 v124, v123
	v_mov_b32_e32 v111, v123
	v_mov_b32_e32 v110, v123
	v_mov_b32_e32 v109, v123
	v_mov_b32_e32 v108, v123
	v_mov_b32_e32 v107, v123
	v_mov_b32_e32 v106, v123
	v_mov_b32_e32 v105, v123
	v_mov_b32_e32 v104, v123
	v_mov_b32_e32 v95, v123
	v_mov_b32_e32 v94, v123
	v_mov_b32_e32 v93, v123
	v_mov_b32_e32 v92, v123
	v_mov_b32_e32 v91, v123
	v_mov_b32_e32 v90, v123
	v_mov_b32_e32 v89, v123
	v_mov_b32_e32 v88, v123
	v_mov_b32_e32 v79, v123
	v_mov_b32_e32 v78, v123
	v_mov_b32_e32 v77, v123
	v_mov_b32_e32 v76, v123
	v_mov_b32_e32 v75, v123
	v_mov_b32_e32 v74, v123
	v_mov_b32_e32 v73, v123
	v_mov_b32_e32 v72, v123
	v_mov_b32_e32 v119, v123
	v_mov_b32_e32 v118, v123
	v_mov_b32_e32 v117, v123
	v_mov_b32_e32 v116, v123
	v_mov_b32_e32 v115, v123
	v_mov_b32_e32 v114, v123
	v_mov_b32_e32 v113, v123
	v_mov_b32_e32 v112, v123
	v_mov_b32_e32 v103, v123
	v_mov_b32_e32 v102, v123
	v_mov_b32_e32 v101, v123
	v_mov_b32_e32 v100, v123
	v_mov_b32_e32 v99, v123
	v_mov_b32_e32 v98, v123
	v_mov_b32_e32 v97, v123
	v_mov_b32_e32 v96, v123
	v_mov_b32_e32 v87, v123
	v_mov_b32_e32 v86, v123
	v_mov_b32_e32 v85, v123
	v_mov_b32_e32 v84, v123
	v_mov_b32_e32 v83, v123
	v_mov_b32_e32 v82, v123
	v_mov_b32_e32 v81, v123
	v_mov_b32_e32 v80, v123
	v_mov_b32_e32 v71, v123
	v_mov_b32_e32 v70, v123
	v_mov_b32_e32 v69, v123
	v_mov_b32_e32 v68, v123
	v_mov_b32_e32 v67, v123
	v_mov_b32_e32 v66, v123
	v_mov_b32_e32 v65, v123
	v_mov_b32_e32 v64, v123
	v_mov_b32_e32 v63, v123
	v_mov_b32_e32 v62, v123
	v_mov_b32_e32 v61, v123
	v_mov_b32_e32 v60, v123
	v_mov_b32_e32 v59, v123
	v_mov_b32_e32 v58, v123
	v_mov_b32_e32 v57, v123
	v_mov_b32_e32 v56, v123
	v_mov_b32_e32 v47, v123
	v_mov_b32_e32 v46, v123
	v_mov_b32_e32 v45, v123
	v_mov_b32_e32 v44, v123
	v_mov_b32_e32 v43, v123
	v_mov_b32_e32 v42, v123
	v_mov_b32_e32 v41, v123
	v_mov_b32_e32 v40, v123
	v_mov_b32_e32 v31, v123
	v_mov_b32_e32 v30, v123
	v_mov_b32_e32 v29, v123
	v_mov_b32_e32 v28, v123
	v_mov_b32_e32 v27, v123
	v_mov_b32_e32 v26, v123
	v_mov_b32_e32 v25, v123
	v_mov_b32_e32 v24, v123
	v_mov_b32_e32 v15, v123
	v_mov_b32_e32 v14, v123
	v_mov_b32_e32 v13, v123
	v_mov_b32_e32 v12, v123
	v_mov_b32_e32 v11, v123
	v_mov_b32_e32 v10, v123
	v_mov_b32_e32 v9, v123
	v_mov_b32_e32 v8, v123
	v_mov_b32_e32 v55, v123
	v_mov_b32_e32 v54, v123
	v_mov_b32_e32 v53, v123
	v_mov_b32_e32 v52, v123
	v_mov_b32_e32 v51, v123
	v_mov_b32_e32 v50, v123
	v_mov_b32_e32 v49, v123
	v_mov_b32_e32 v48, v123
	v_mov_b32_e32 v39, v123
	v_mov_b32_e32 v38, v123
	v_mov_b32_e32 v37, v123
	v_mov_b32_e32 v36, v123
	v_mov_b32_e32 v35, v123
	v_mov_b32_e32 v34, v123
	v_mov_b32_e32 v33, v123
	v_mov_b32_e32 v32, v123
	v_mov_b32_e32 v23, v123
	v_mov_b32_e32 v22, v123
	v_mov_b32_e32 v21, v123
	v_mov_b32_e32 v20, v123
	v_mov_b32_e32 v19, v123
	v_mov_b32_e32 v18, v123
	v_mov_b32_e32 v17, v123
	v_mov_b32_e32 v16, v123
	v_mov_b32_e32 v7, v123
	v_mov_b32_e32 v6, v123
	v_mov_b32_e32 v5, v123
	v_mov_b32_e32 v4, v123
	v_mov_b32_e32 v3, v123
	v_mov_b32_e32 v2, v123
	v_mov_b32_e32 v1, v123
	v_mov_b32_e32 v0, v123
	s_cbranch_vccnz .LBB0_303
	s_and_b64 s[6:7], s[6:7], exec
	s_cselect_b32 s16, s47, s11
	s_cselect_b32 s17, s46, s10
	s_add_u32 s18, s10, 0x100
	s_addc_u32 s19, s11, 0
	s_mov_b32 s10, 0

; template <class Epi>
; DI void gemm_phase(LAS unsigned char* lds, const Gemm g, const StaticOrder& S, const Epi& E) {
;     ...
;     f32x4 acc[2][2][4][2];
; #pragma unroll
;     for (int a = 0; a < 2; ++a)
; #pragma unroll
;         for (int b = 0; b < 2; ++b)
; #pragma unroll
;             for (int m = 0; m < 4; ++m)
; #pragma unroll
;                 for (int n = 0; n < 2; ++n) acc[a][b][m][n] = (f32x4){0.f, 0.f, 0.f, 0.f};
; __global__ void __launch_bounds__(512, 2) mk_fwd(Params prm) {
;     ...
;         { pg8::Gemm g{(const bf16_t*)(ws + WS_PROJ) + PJ_CKV, (const bf16_t*)(ws + WS_WKVUP), T, 2048, 512, DIN_P, 512}; pg8::StaticOrder So; So.init(T, 2048, G, cid);
;           EpiUp<1> E{ssq + T, 1.0f / 512.0f, 1.0f, (bf16_t*)(ws + WS_KN), KNW, cs, nullptr};
;           pg8::gemm_phase<EpiUp<1>>(lds, g, So, E); }
.LBB0_327:
	s_ashr_i32 s25, s24, 31
	s_lshl_b64 s[28:29], s[24:25], 18
	s_add_u32 s28, s42, s28
	v_mov_b32_e32 v123, 0
	s_addc_u32 s29, s43, s29
	s_andn2_b64 vcc, exec, s[18:19]
	v_mov_b32_e32 v122, v123
	v_mov_b32_e32 v121, v123
	v_mov_b32_e32 v120, v123
	v_mov_b32_e32 v127, v123
	v_mov_b32_e32 v126, v123
	v_mov_b32_e32 v125, v123
	v_mov_b32_e32 v124, v123
	v_mov_b32_e32 v111, v123
	v_mov_b32_e32 v110, v123
	v_mov_b32_e32 v109, v123
	v_mov_b32_e32 v108, v123
	v_mov_b32_e32 v107, v123
	v_mov_b32_e32 v106, v123
	v_mov_b32_e32 v105, v123
	v_mov_b32_e32 v104, v123
	v_mov_b32_e32 v95, v123
	v_mov_b32_e32 v94, v123
	v_mov_b32_e32 v93, v123
	v_mov_b32_e32 v92, v123
	v_mov_b32_e32 v91, v123
	v_mov_b32_e32 v90, v123
	v_mov_b32_e32 v89, v123
	v_mov_b32_e32 v88, v123
	v_mov_b32_e32 v79, v123
	v_mov_b32_e32 v78, v123
	v_mov_b32_e32 v77, v123
	v_mov_b32_e32 v76, v123
	v_mov_b32_e32 v75, v123
	v_mov_b32_e32 v74, v123
	v_mov_b32_e32 v73, v123
	v_mov_b32_e32 v72, v123
	v_mov_b32_e32 v119, v123
	v_mov_b32_e32 v118, v123
	v_mov_b32_e32 v117, v123
	v_mov_b32_e32 v116, v123
	v_mov_b32_e32 v115, v123
	v_mov_b32_e32 v114, v123
	v_mov_b32_e32 v113, v123
	v_mov_b32_e32 v112, v123
	v_mov_b32_e32 v103, v123
	v_mov_b32_e32 v102, v123
	v_mov_b32_e32 v101, v123
	v_mov_b32_e32 v100, v123
	v_mov_b32_e32 v99, v123
	v_mov_b32_e32 v98, v123
	v_mov_b32_e32 v97, v123
	v_mov_b32_e32 v96, v123
	v_mov_b32_e32 v87, v123
	v_mov_b32_e32 v86, v123
	v_mov_b32_e32 v85, v123
	v_mov_b32_e32 v84, v123
	v_mov_b32_e32 v83, v123
	v_mov_b32_e32 v82, v123
	v_mov_b32_e32 v81, v123
	v_mov_b32_e32 v80, v123
	v_mov_b32_e32 v71, v123
	v_mov_b32_e32 v70, v123
	v_mov_b32_e32 v69, v123
	v_mov_b32_e32 v68, v123
	v_mov_b32_e32 v67, v123
	v_mov_b32_e32 v66, v123
	v_mov_b32_e32 v65, v123
	v_mov_b32_e32 v64, v123
	v_mov_b32_e32 v63, v123
	v_mov_b32_e32 v62, v123
	v_mov_b32_e32 v61, v123
	v_mov_b32_e32 v60, v123
	v_mov_b32_e32 v59, v123
	v_mov_b32_e32 v58, v123
	v_mov_b32_e32 v57, v123
	v_mov_b32_e32 v56, v123
	v_mov_b32_e32 v47, v123
	v_mov_b32_e32 v46, v123
	v_mov_b32_e32 v45, v123
	v_mov_b32_e32 v44, v123
	v_mov_b32_e32 v43, v123
	v_mov_b32_e32 v42, v123
	v_mov_b32_e32 v41, v123
	v_mov_b32_e32 v40, v123
	v_mov_b32_e32 v31, v123
	v_mov_b32_e32 v30, v123
	v_mov_b32_e32 v29, v123
	v_mov_b32_e32 v28, v123
	v_mov_b32_e32 v27, v123
	v_mov_b32_e32 v26, v123
	v_mov_b32_e32 v25, v123
	v_mov_b32_e32 v24, v123
	v_mov_b32_e32 v15, v123
	v_mov_b32_e32 v14, v123
	v_mov_b32_e32 v13, v123
	v_mov_b32_e32 v12, v123
	v_mov_b32_e32 v11, v123
	v_mov_b32_e32 v10, v123
	v_mov_b32_e32 v9, v123
	v_mov_b32_e32 v8, v123
	v_mov_b32_e32 v55, v123
	v_mov_b32_e32 v54, v123
	v_mov_b32_e32 v53, v123
	v_mov_b32_e32 v52, v123
	v_mov_b32_e32 v51, v123
	v_mov_b32_e32 v50, v123
	v_mov_b32_e32 v49, v123
	v_mov_b32_e32 v48, v123
	v_mov_b32_e32 v39, v123
	v_mov_b32_e32 v38, v123
	v_mov_b32_e32 v37, v123
	v_mov_b32_e32 v36, v123
	v_mov_b32_e32 v35, v123
	v_mov_b32_e32 v34, v123
	v_mov_b32_e32 v33, v123
	v_mov_b32_e32 v32, v123
	v_mov_b32_e32 v23, v123
	v_mov_b32_e32 v22, v123
	v_mov_b32_e32 v21, v123
	v_mov_b32_e32 v20, v123
	v_mov_b32_e32 v19, v123
	v_mov_b32_e32 v18, v123
	v_mov_b32_e32 v17, v123
	v_mov_b32_e32 v16, v123
	v_mov_b32_e32 v7, v123
	v_mov_b32_e32 v6, v123
	v_mov_b32_e32 v5, v123
	v_mov_b32_e32 v4, v123
	v_mov_b32_e32 v3, v123
	v_mov_b32_e32 v2, v123
	v_mov_b32_e32 v1, v123
	v_mov_b32_e32 v0, v123
	s_cbranch_vccnz .LBB0_330
	s_and_b64 s[6:7], s[6:7], exec
	s_cselect_b32 s25, s29, s31
	s_cselect_b32 s70, s28, s30
	s_add_u32 s71, s30, 0x100
	s_addc_u32 s72, s31, 0
	s_mov_b32 s30, 0

; template <class Epi>
; DI void gemm_phase(LAS unsigned char* lds, const Gemm g, const StaticOrder& S, const Epi& E) {
;     ...
;     f32x4 acc[2][2][4][2];
; #pragma unroll
;     for (int a = 0; a < 2; ++a)
; #pragma unroll
;         for (int b = 0; b < 2; ++b)
; #pragma unroll
;             for (int m = 0; m < 4; ++m)
; #pragma unroll
;                 for (int n = 0; n < 2; ++n) acc[a][b][m][n] = (f32x4){0.f, 0.f, 0.f, 0.f};
; __global__ void __launch_bounds__(512, 2) mk_fwd(Params prm) {
;     ...
;         { pg8::Gemm g{(const bf16_t*)(ws + WS_WKVUP) + (size_t)2048 * 512, (const bf16_t*)(ws + WS_PROJ) + PJ_CKV, 2048, T, 512, 512, DIN_P}; pg8::StaticOrder So; So.init(2048, T, G, cid);
;           EpiVt E{(bf16_t*)(ws + WS_VT), 2048, ssq + T, 1.0f / 512.0f};
;           pg8::gemm_phase<EpiVt>(lds, g, So, E); }
.LBB0_350:
	s_ashr_i32 s59, s58, 31
	s_lshl_b64 s[12:13], s[58:59], 18
	s_add_u32 s62, s67, s12
	v_mov_b32_e32 v127, 0
	s_addc_u32 s63, s68, s13
	s_andn2_b64 vcc, exec, s[46:47]
	v_mov_b32_e32 v126, v127
	v_mov_b32_e32 v125, v127
	v_mov_b32_e32 v124, v127
	v_mov_b32_e32 v123, v127
	v_mov_b32_e32 v122, v127
	v_mov_b32_e32 v121, v127
	v_mov_b32_e32 v120, v127
	v_mov_b32_e32 v111, v127
	v_mov_b32_e32 v110, v127
	v_mov_b32_e32 v109, v127
	v_mov_b32_e32 v108, v127
	v_mov_b32_e32 v107, v127
	v_mov_b32_e32 v106, v127
	v_mov_b32_e32 v105, v127
	v_mov_b32_e32 v104, v127
	v_mov_b32_e32 v95, v127
	v_mov_b32_e32 v94, v127
	v_mov_b32_e32 v93, v127
	v_mov_b32_e32 v92, v127
	v_mov_b32_e32 v91, v127
	v_mov_b32_e32 v90, v127
	v_mov_b32_e32 v89, v127
	v_mov_b32_e32 v88, v127
	v_mov_b32_e32 v79, v127
	v_mov_b32_e32 v78, v127
	v_mov_b32_e32 v77, v127
	v_mov_b32_e32 v76, v127
	v_mov_b32_e32 v75, v127
	v_mov_b32_e32 v74, v127
	v_mov_b32_e32 v73, v127
	v_mov_b32_e32 v72, v127
	v_mov_b32_e32 v119, v127
	v_mov_b32_e32 v118, v127
	v_mov_b32_e32 v117, v127
	v_mov_b32_e32 v116, v127
	v_mov_b32_e32 v115, v127
	v_mov_b32_e32 v114, v127
	v_mov_b32_e32 v113, v127
	v_mov_b32_e32 v112, v127
	v_mov_b32_e32 v103, v127
	v_mov_b32_e32 v102, v127
	v_mov_b32_e32 v101, v127
	v_mov_b32_e32 v100, v127
	v_mov_b32_e32 v99, v127
	v_mov_b32_e32 v98, v127
	v_mov_b32_e32 v97, v127
	v_mov_b32_e32 v96, v127
	v_mov_b32_e32 v87, v127
	v_mov_b32_e32 v86, v127
	v_mov_b32_e32 v85, v127
	v_mov_b32_e32 v84, v127
	v_mov_b32_e32 v83, v127
	v_mov_b32_e32 v82, v127
	v_mov_b32_e32 v81, v127
	v_mov_b32_e32 v80, v127
	v_mov_b32_e32 v71, v127
	v_mov_b32_e32 v70, v127
	v_mov_b32_e32 v69, v127
	v_mov_b32_e32 v68, v127
	v_mov_b32_e32 v67, v127
	v_mov_b32_e32 v66, v127
	v_mov_b32_e32 v65, v127
	v_mov_b32_e32 v64, v127
	v_mov_b32_e32 v63, v127
	v_mov_b32_e32 v62, v127
	v_mov_b32_e32 v61, v127
	v_mov_b32_e32 v60, v127
	v_mov_b32_e32 v59, v127
	v_mov_b32_e32 v58, v127
	v_mov_b32_e32 v57, v127
	v_mov_b32_e32 v56, v127
	v_mov_b32_e32 v47, v127
	v_mov_b32_e32 v46, v127
	v_mov_b32_e32 v45, v127
	v_mov_b32_e32 v44, v127
	v_mov_b32_e32 v43, v127
	v_mov_b32_e32 v42, v127
	v_mov_b32_e32 v41, v127
	v_mov_b32_e32 v40, v127
	v_mov_b32_e32 v31, v127
	v_mov_b32_e32 v30, v127
	v_mov_b32_e32 v29, v127
	v_mov_b32_e32 v28, v127
	v_mov_b32_e32 v27, v127
	v_mov_b32_e32 v26, v127
	v_mov_b32_e32 v25, v127
	v_mov_b32_e32 v24, v127
	v_mov_b32_e32 v15, v127
	v_mov_b32_e32 v14, v127
	v_mov_b32_e32 v13, v127
	v_mov_b32_e32 v12, v127
	v_mov_b32_e32 v11, v127
	v_mov_b32_e32 v10, v127
	v_mov_b32_e32 v9, v127
	v_mov_b32_e32 v8, v127
	v_mov_b32_e32 v55, v127
	v_mov_b32_e32 v54, v127
	v_mov_b32_e32 v53, v127
	v_mov_b32_e32 v52, v127
	v_mov_b32_e32 v51, v127
	v_mov_b32_e32 v50, v127
	v_mov_b32_e32 v49, v127
	v_mov_b32_e32 v48, v127
	v_mov_b32_e32 v39, v127
	v_mov_b32_e32 v38, v127
	v_mov_b32_e32 v37, v127
	v_mov_b32_e32 v36, v127
	v_mov_b32_e32 v35, v127
	v_mov_b32_e32 v34, v127
	v_mov_b32_e32 v33, v127
	v_mov_b32_e32 v32, v127
	v_mov_b32_e32 v23, v127
	v_mov_b32_e32 v22, v127
	v_mov_b32_e32 v21, v127
	v_mov_b32_e32 v20, v127
	v_mov_b32_e32 v19, v127
	v_mov_b32_e32 v18, v127
	v_mov_b32_e32 v17, v127
	v_mov_b32_e32 v16, v127
	v_mov_b32_e32 v7, v127
	v_mov_b32_e32 v6, v127
	v_mov_b32_e32 v5, v127
	v_mov_b32_e32 v4, v127
	v_mov_b32_e32 v3, v127
	v_mov_b32_e32 v2, v127
	v_mov_b32_e32 v1, v127
	v_mov_b32_e32 v0, v127
	s_cbranch_vccnz .LBB0_353
	s_and_b64 s[6:7], s[6:7], exec
	s_cselect_b32 s12, s63, s11
	s_cselect_b32 s13, s62, s10
	s_add_u32 s6, s10, 0x20080
	s_addc_u32 s7, s11, 0
	s_add_u32 s14, s8, 0x100
	s_addc_u32 s15, s9, 0
	s_mov_b32 s8, 0

; #define REPSYNC(k) do { if (_r + 1 < NREP(k)) cg::this_grid().sync(); } while (0)
; template <class Epi>
; DI void gemm_phase(LAS unsigned char* lds, const Gemm g, const StaticOrder& S, const Epi& E) {
;     ...
;     f32x4 acc[2][2][4][2];
; #pragma unroll
;     for (int a = 0; a < 2; ++a)
; #pragma unroll
;         for (int b = 0; b < 2; ++b)
; #pragma unroll
;             for (int m = 0; m < 4; ++m)
; #pragma unroll
;                 for (int n = 0; n < 2; ++n) acc[a][b][m][n] = (f32x4){0.f, 0.f, 0.f, 0.f};
; __global__ void __launch_bounds__(512, 2) mk_fwd(Params prm) {
;     ...
;         pg8::Gemm g{(const bf16_t*)(ws + WS_R0), (const bf16_t*)(ws + WS_WGU), T, 2 * DFF, D, D, D}; pg8::StaticOrder So; So.init(T, 2 * DFF, G, cid);
;         EpiSwiglu E{(bf16_t*)(ws + WS_ACT)};
;         pg8::gemm_phase<EpiSwiglu>(lds, g, So, E); REPSYNC(7); }
.LBB0_703:
	s_ashr_i32 s19, s18, 31
	s_lshl_b64 s[20:21], s[18:19], 21
	s_add_u32 s20, s33, s20
	s_addc_u32 s21, s34, s21
	s_ashr_i32 s17, s16, 31
	s_lshl_b64 s[22:23], s[16:17], 21
	s_add_u32 s22, s35, s22
	v_mov_b32_e32 v127, 0
	s_addc_u32 s23, s38, s23
	s_and_b64 vcc, exec, s[4:5]
	v_mov_b32_e32 v126, v127
	v_mov_b32_e32 v125, v127
	v_mov_b32_e32 v124, v127
	v_mov_b32_e32 v119, v127
	v_mov_b32_e32 v118, v127
	v_mov_b32_e32 v117, v127
	v_mov_b32_e32 v116, v127
	v_mov_b32_e32 v111, v127
	v_mov_b32_e32 v110, v127
	v_mov_b32_e32 v109, v127
	v_mov_b32_e32 v108, v127
	v_mov_b32_e32 v103, v127
	v_mov_b32_e32 v102, v127
	v_mov_b32_e32 v101, v127
	v_mov_b32_e32 v100, v127
	v_mov_b32_e32 v95, v127
	v_mov_b32_e32 v94, v127
	v_mov_b32_e32 v93, v127
	v_mov_b32_e32 v92, v127
	v_mov_b32_e32 v87, v127
	v_mov_b32_e32 v86, v127
	v_mov_b32_e32 v85, v127
	v_mov_b32_e32 v84, v127
	v_mov_b32_e32 v79, v127
	v_mov_b32_e32 v78, v127
	v_mov_b32_e32 v77, v127
	v_mov_b32_e32 v76, v127
	v_mov_b32_e32 v71, v127
	v_mov_b32_e32 v70, v127
	v_mov_b32_e32 v69, v127
	v_mov_b32_e32 v68, v127
	v_mov_b32_e32 v123, v127
	v_mov_b32_e32 v122, v127
	v_mov_b32_e32 v121, v127
	v_mov_b32_e32 v120, v127
	v_mov_b32_e32 v115, v127
	v_mov_b32_e32 v114, v127
	v_mov_b32_e32 v113, v127
	v_mov_b32_e32 v112, v127
	v_mov_b32_e32 v107, v127
	v_mov_b32_e32 v106, v127
	v_mov_b32_e32 v105, v127
	v_mov_b32_e32 v104, v127
	v_mov_b32_e32 v99, v127
	v_mov_b32_e32 v98, v127
	v_mov_b32_e32 v97, v127
	v_mov_b32_e32 v96, v127
	v_mov_b32_e32 v91, v127
	v_mov_b32_e32 v90, v127
	v_mov_b32_e32 v89, v127
	v_mov_b32_e32 v88, v127
	v_mov_b32_e32 v83, v127
	v_mov_b32_e32 v82, v127
	v_mov_b32_e32 v81, v127
	v_mov_b32_e32 v80, v127
	v_mov_b32_e32 v75, v127
	v_mov_b32_e32 v74, v127
	v_mov_b32_e32 v73, v127
	v_mov_b32_e32 v72, v127
	v_mov_b32_e32 v67, v127
	v_mov_b32_e32 v66, v127
	v_mov_b32_e32 v65, v127
	v_mov_b32_e32 v64, v127
	v_mov_b32_e32 v63, v127
	v_mov_b32_e32 v62, v127
	v_mov_b32_e32 v61, v127
	v_mov_b32_e32 v60, v127
	v_mov_b32_e32 v55, v127
	v_mov_b32_e32 v54, v127
	v_mov_b32_e32 v53, v127
	v_mov_b32_e32 v52, v127
	v_mov_b32_e32 v47, v127
	v_mov_b32_e32 v46, v127
	v_mov_b32_e32 v45, v127
	v_mov_b32_e32 v44, v127
	v_mov_b32_e32 v39, v127
	v_mov_b32_e32 v38, v127
	v_mov_b32_e32 v37, v127
	v_mov_b32_e32 v36, v127
	v_mov_b32_e32 v31, v127
	v_mov_b32_e32 v30, v127
	v_mov_b32_e32 v29, v127
	v_mov_b32_e32 v28, v127
	v_mov_b32_e32 v23, v127
	v_mov_b32_e32 v22, v127
	v_mov_b32_e32 v21, v127
	v_mov_b32_e32 v20, v127
	v_mov_b32_e32 v15, v127
	v_mov_b32_e32 v14, v127
	v_mov_b32_e32 v13, v127
	v_mov_b32_e32 v12, v127
	v_mov_b32_e32 v7, v127
	v_mov_b32_e32 v6, v127
	v_mov_b32_e32 v5, v127
	v_mov_b32_e32 v4, v127
	v_mov_b32_e32 v59, v127
	v_mov_b32_e32 v58, v127
	v_mov_b32_e32 v57, v127
	v_mov_b32_e32 v56, v127
	v_mov_b32_e32 v51, v127
	v_mov_b32_e32 v50, v127
	v_mov_b32_e32 v49, v127
	v_mov_b32_e32 v48, v127
	v_mov_b32_e32 v43, v127
	v_mov_b32_e32 v42, v127
	v_mov_b32_e32 v41, v127
	v_mov_b32_e32 v40, v127
	v_mov_b32_e32 v35, v127
	v_mov_b32_e32 v34, v127
	v_mov_b32_e32 v33, v127
	v_mov_b32_e32 v32, v127
	v_mov_b32_e32 v27, v127
	v_mov_b32_e32 v26, v127
	v_mov_b32_e32 v25, v127
	v_mov_b32_e32 v24, v127
	v_mov_b32_e32 v19, v127
	v_mov_b32_e32 v18, v127
	v_mov_b32_e32 v17, v127
	v_mov_b32_e32 v16, v127
	v_mov_b32_e32 v11, v127
	v_mov_b32_e32 v10, v127
	v_mov_b32_e32 v9, v127
	v_mov_b32_e32 v8, v127
	v_mov_b32_e32 v3, v127
	v_mov_b32_e32 v2, v127
	v_mov_b32_e32 v1, v127
	v_mov_b32_e32 v0, v127
	s_cbranch_vccnz .LBB0_706
	s_and_b64 s[30:31], s[6:7], exec
	s_cselect_b32 s17, s21, s27
	s_cselect_b32 s19, s20, s26
	s_cselect_b32 s59, s23, s29
	s_cselect_b32 s60, s22, s28
	s_add_u32 s26, s26, 0x100080
	s_addc_u32 s27, s27, 0
	s_add_u32 s61, s28, 0x100
	s_addc_u32 s62, s29, 0
	s_mov_b32 s28, 0

; template <class Epi>
; DI void gemm_phase(LAS unsigned char* lds, const Gemm g, const StaticOrder& S, const Epi& E) {
;     ...
;     f32x4 acc[2][2][4][2];
; #pragma unroll
;     for (int a = 0; a < 2; ++a)
; #pragma unroll
;         for (int b = 0; b < 2; ++b)
; #pragma unroll
;             for (int m = 0; m < 4; ++m)
; #pragma unroll
;                 for (int n = 0; n < 2; ++n) acc[a][b][m][n] = (f32x4){0.f, 0.f, 0.f, 0.f};
; __global__ void __launch_bounds__(512, 2) mk_fwd(Params prm) {
;     ...
;                 pg8::Gemm g{(const bf16_t*)(ws + WS_PB), (const bf16_t*)(ws + WS_WPP), T, D, PLE, PLE, PLE}; pg8::StaticOrder So; So.init(T, D, gp, cp);
;                 EpiBf16 E{(bf16_t*)(ws + WS_PP), D};
;                 pg8::gemm_phase<EpiBf16>(lds, g, So, E);
.LBB0_725:
	s_ashr_i32 s27, s26, 31
	s_lshl_b64 s[28:29], s[26:27], 17
	s_add_u32 s28, s42, s28
	s_addc_u32 s29, s43, s29
	s_ashr_i32 s25, s24, 31
	s_lshl_b64 s[30:31], s[24:25], 17
	s_add_u32 s30, s46, s30
	v_mov_b32_e32 v123, 0
	s_addc_u32 s31, s47, s31
	s_andn2_b64 vcc, exec, s[12:13]
	v_mov_b32_e32 v122, v123
	v_mov_b32_e32 v121, v123
	v_mov_b32_e32 v120, v123
	v_mov_b32_e32 v127, v123
	v_mov_b32_e32 v126, v123
	v_mov_b32_e32 v125, v123
	v_mov_b32_e32 v124, v123
	v_mov_b32_e32 v111, v123
	v_mov_b32_e32 v110, v123
	v_mov_b32_e32 v109, v123
	v_mov_b32_e32 v108, v123
	v_mov_b32_e32 v107, v123
	v_mov_b32_e32 v106, v123
	v_mov_b32_e32 v105, v123
	v_mov_b32_e32 v104, v123
	v_mov_b32_e32 v95, v123
	v_mov_b32_e32 v94, v123
	v_mov_b32_e32 v93, v123
	v_mov_b32_e32 v92, v123
	v_mov_b32_e32 v91, v123
	v_mov_b32_e32 v90, v123
	v_mov_b32_e32 v89, v123
	v_mov_b32_e32 v88, v123
	v_mov_b32_e32 v79, v123
	v_mov_b32_e32 v78, v123
	v_mov_b32_e32 v77, v123
	v_mov_b32_e32 v76, v123
	v_mov_b32_e32 v75, v123
	v_mov_b32_e32 v74, v123
	v_mov_b32_e32 v73, v123
	v_mov_b32_e32 v72, v123
	v_mov_b32_e32 v119, v123
	v_mov_b32_e32 v118, v123
	v_mov_b32_e32 v117, v123
	v_mov_b32_e32 v116, v123
	v_mov_b32_e32 v115, v123
	v_mov_b32_e32 v114, v123
	v_mov_b32_e32 v113, v123
	v_mov_b32_e32 v112, v123
	v_mov_b32_e32 v103, v123
	v_mov_b32_e32 v102, v123
	v_mov_b32_e32 v101, v123
	v_mov_b32_e32 v100, v123
	v_mov_b32_e32 v99, v123
	v_mov_b32_e32 v98, v123
	v_mov_b32_e32 v97, v123
	v_mov_b32_e32 v96, v123
	v_mov_b32_e32 v87, v123
	v_mov_b32_e32 v86, v123
	v_mov_b32_e32 v85, v123
	v_mov_b32_e32 v84, v123
	v_mov_b32_e32 v83, v123
	v_mov_b32_e32 v82, v123
	v_mov_b32_e32 v81, v123
	v_mov_b32_e32 v80, v123
	v_mov_b32_e32 v71, v123
	v_mov_b32_e32 v70, v123
	v_mov_b32_e32 v69, v123
	v_mov_b32_e32 v68, v123
	v_mov_b32_e32 v67, v123
	v_mov_b32_e32 v66, v123
	v_mov_b32_e32 v65, v123
	v_mov_b32_e32 v64, v123
	v_mov_b32_e32 v63, v123
	v_mov_b32_e32 v62, v123
	v_mov_b32_e32 v61, v123
	v_mov_b32_e32 v60, v123
	v_mov_b32_e32 v59, v123
	v_mov_b32_e32 v58, v123
	v_mov_b32_e32 v57, v123
	v_mov_b32_e32 v56, v123
	v_mov_b32_e32 v47, v123
	v_mov_b32_e32 v46, v123
	v_mov_b32_e32 v45, v123
	v_mov_b32_e32 v44, v123
	v_mov_b32_e32 v43, v123
	v_mov_b32_e32 v42, v123
	v_mov_b32_e32 v41, v123
	v_mov_b32_e32 v40, v123
	v_mov_b32_e32 v31, v123
	v_mov_b32_e32 v30, v123
	v_mov_b32_e32 v29, v123
	v_mov_b32_e32 v28, v123
	v_mov_b32_e32 v27, v123
	v_mov_b32_e32 v26, v123
	v_mov_b32_e32 v25, v123
	v_mov_b32_e32 v24, v123
	v_mov_b32_e32 v15, v123
	v_mov_b32_e32 v14, v123
	v_mov_b32_e32 v13, v123
	v_mov_b32_e32 v12, v123
	v_mov_b32_e32 v11, v123
	v_mov_b32_e32 v10, v123
	v_mov_b32_e32 v9, v123
	v_mov_b32_e32 v8, v123
	v_mov_b32_e32 v55, v123
	v_mov_b32_e32 v54, v123
	v_mov_b32_e32 v53, v123
	v_mov_b32_e32 v52, v123
	v_mov_b32_e32 v51, v123
	v_mov_b32_e32 v50, v123
	v_mov_b32_e32 v49, v123
	v_mov_b32_e32 v48, v123
	v_mov_b32_e32 v39, v123
	v_mov_b32_e32 v38, v123
	v_mov_b32_e32 v37, v123
	v_mov_b32_e32 v36, v123
	v_mov_b32_e32 v35, v123
	v_mov_b32_e32 v34, v123
	v_mov_b32_e32 v33, v123
	v_mov_b32_e32 v32, v123
	v_mov_b32_e32 v23, v123
	v_mov_b32_e32 v22, v123
	v_mov_b32_e32 v21, v123
	v_mov_b32_e32 v20, v123
	v_mov_b32_e32 v19, v123
	v_mov_b32_e32 v18, v123
	v_mov_b32_e32 v17, v123
	v_mov_b32_e32 v16, v123
	v_mov_b32_e32 v7, v123
	v_mov_b32_e32 v6, v123
	v_mov_b32_e32 v5, v123
	v_mov_b32_e32 v4, v123
	v_mov_b32_e32 v3, v123
	v_mov_b32_e32 v2, v123
	v_mov_b32_e32 v1, v123
	v_mov_b32_e32 v0, v123
	s_cbranch_vccnz .LBB0_728
	s_and_b64 s[40:41], s[4:5], exec
	s_cselect_b32 s25, s29, s35
	s_cselect_b32 s27, s28, s34
	s_cselect_b32 s70, s31, s39
	s_cselect_b32 s71, s30, s38
	s_add_u32 s34, s34, 0x10080
	s_addc_u32 s35, s35, 0
	s_add_u32 s72, s38, 0x100
	s_addc_u32 s73, s39, 0
	s_mov_b32 s38, 0

; #define PG8_STAGE(bufoff, gbase, voff) do { _Pragma("unroll") for (int _i = 0; _i < 2; ++_i) \
;         __builtin_amdgcn_global_load_lds((const unsigned*)((const char*)(gbase) + (voff)[_i]), (LAS unsigned*)(lds + (bufoff) + ldsw + _i * 8192), 16, 0, 0); } while (0)
; #define PG8_LDA(dst, b, h) do { _Pragma("unroll") for (int m = 0; m < 4; ++m) _Pragma("unroll") for (int k = 0; k < 2; ++k) dst[m][k] = *(const LAS bf16x8*)(lds + PG8_SA(b, h) + aoff + m * 2048 + k * 1024); } while (0)
; #define PG8_LDB(dst, b, h) do { _Pragma("unroll") for (int n = 0; n < 2; ++n) _Pragma("unroll") for (int k = 0; k < 2; ++k) dst[n][k] = *(const LAS bf16x8*)(lds + PG8_SB(b, h) + boff + n * 2048 + k * 1024); } while (0)
; #define PG8_WAIT_V(n) asm volatile("s_waitcnt vmcnt(" #n ")" ::: "memory")
; #define PG8_WAIT_L(n) asm volatile("s_waitcnt lgkmcnt(" #n ")" ::: "memory")
; #define PG8_BAR __builtin_amdgcn_s_barrier()
; #define PG8_SCHED __builtin_amdgcn_sched_barrier(0)
; template <class Epi>
; DI void gemm_phase(LAS unsigned char* lds, const Gemm g, const StaticOrder& S, const Epi& E) {
;     ...
;     for (;;) {
;         const bool has_next = S.next(ui + 1, nxt);
;         const char* nA = has_next ? (const char*)g.A + (size_t)nxt.pm * tstepA + PG8_KOFF(nxt) : cA; const char* nB = has_next ? (const char*)g.Bt + (size_t)nxt.pn * tstepB + PG8_KOFF(nxt) : cB;
;         for (int t = 0; t < nt; t += 2) {
;             const bool last = (t == nt - 2);
;             const char* a1 = cA + (size_t)(t + 1) * kstep;
;             const char* a2 = last ? nA : cA + (size_t)(t + 2) * kstep; const char* b2 = last ? nB : cB + (size_t)(t + 2) * kstep;
;             const char* a3 = a2 + kstep; const char* b3 = b2 + kstep;
;             PG8_LDB(B0, 0, 0); PG8_LDB(B1, 0, 1); PG8_SCHED; PG8_LDA(At, 0, 0); PG8_STAGE(PG8_SA(1, 1), a1 + hstepA, voffA);
;             PG8_WAIT_V(8); PG8_WAIT_L(0); PG8_BAR; PG8_MMA(0, 0, At, B0); PG8_MMA(0, 1, At, B1); PG8_BAR; PG8_SCHED;
; __global__ void __launch_bounds__(512, 2) mk_fwd(Params prm) {
;     ...
;         pg8::Gemm g{(const bf16_t*)(ws + WS_ACT), (const bf16_t*)(ws + WS_WDN), T, D, DFF, DFF, DFF}; pg8::StaticOrder So; So.init(T, D, G, cid);
;         EpiBf16Ssq<false> E{(bf16_t*)(ws + WS_F), ssq + 5 * T + (_r ? 6 * T : 0), nullptr, nullptr};
;         pg8::gemm_phase<EpiBf16Ssq<false>>(lds, g, So, E); REPSYNC(8); }
.LBB0_811:
	v_mov_b32_e32 v127, 0
	s_andn2_b64 vcc, exec, s[18:19]
	v_mov_b32_e32 v126, v127
	v_mov_b32_e32 v125, v127
	v_mov_b32_e32 v124, v127
	v_mov_b32_e32 v123, v127
	v_mov_b32_e32 v122, v127
	v_mov_b32_e32 v121, v127
	v_mov_b32_e32 v120, v127
	v_mov_b32_e32 v111, v127
	v_mov_b32_e32 v110, v127
	v_mov_b32_e32 v109, v127
	v_mov_b32_e32 v108, v127
	v_mov_b32_e32 v107, v127
	v_mov_b32_e32 v106, v127
	v_mov_b32_e32 v105, v127
	v_mov_b32_e32 v104, v127
	v_mov_b32_e32 v95, v127
	v_mov_b32_e32 v94, v127
	v_mov_b32_e32 v93, v127
	v_mov_b32_e32 v92, v127
	v_mov_b32_e32 v91, v127
	v_mov_b32_e32 v90, v127
	v_mov_b32_e32 v89, v127
	v_mov_b32_e32 v88, v127
	v_mov_b32_e32 v79, v127
	v_mov_b32_e32 v78, v127
	v_mov_b32_e32 v77, v127
	v_mov_b32_e32 v76, v127
	v_mov_b32_e32 v75, v127
	v_mov_b32_e32 v74, v127
	v_mov_b32_e32 v73, v127
	v_mov_b32_e32 v72, v127
	v_mov_b32_e32 v119, v127
	v_mov_b32_e32 v118, v127
	v_mov_b32_e32 v117, v127
	v_mov_b32_e32 v116, v127
	v_mov_b32_e32 v115, v127
	v_mov_b32_e32 v114, v127
	v_mov_b32_e32 v113, v127
	v_mov_b32_e32 v112, v127
	v_mov_b32_e32 v103, v127
	v_mov_b32_e32 v102, v127
	v_mov_b32_e32 v101, v127
	v_mov_b32_e32 v100, v127
	v_mov_b32_e32 v99, v127
	v_mov_b32_e32 v98, v127
	v_mov_b32_e32 v97, v127
	v_mov_b32_e32 v96, v127
	v_mov_b32_e32 v87, v127
	v_mov_b32_e32 v86, v127
	v_mov_b32_e32 v85, v127
	v_mov_b32_e32 v84, v127
	v_mov_b32_e32 v83, v127
	v_mov_b32_e32 v82, v127
	v_mov_b32_e32 v81, v127
	v_mov_b32_e32 v80, v127
	v_mov_b32_e32 v71, v127
	v_mov_b32_e32 v70, v127
	v_mov_b32_e32 v69, v127
	v_mov_b32_e32 v68, v127
	v_mov_b32_e32 v67, v127
	v_mov_b32_e32 v66, v127
	v_mov_b32_e32 v65, v127
	v_mov_b32_e32 v64, v127
	v_mov_b32_e32 v63, v127
	v_mov_b32_e32 v62, v127
	v_mov_b32_e32 v61, v127
	v_mov_b32_e32 v60, v127
	v_mov_b32_e32 v59, v127
	v_mov_b32_e32 v58, v127
	v_mov_b32_e32 v57, v127
	v_mov_b32_e32 v56, v127
	v_mov_b32_e32 v47, v127
	v_mov_b32_e32 v46, v127
	v_mov_b32_e32 v45, v127
	v_mov_b32_e32 v44, v127
	v_mov_b32_e32 v43, v127
	v_mov_b32_e32 v42, v127
	v_mov_b32_e32 v41, v127
	v_mov_b32_e32 v40, v127
	v_mov_b32_e32 v31, v127
	v_mov_b32_e32 v30, v127
	v_mov_b32_e32 v29, v127
	v_mov_b32_e32 v28, v127
	v_mov_b32_e32 v27, v127
	v_mov_b32_e32 v26, v127
	v_mov_b32_e32 v25, v127
	v_mov_b32_e32 v24, v127
	v_mov_b32_e32 v15, v127
	v_mov_b32_e32 v14, v127
	v_mov_b32_e32 v13, v127
	v_mov_b32_e32 v12, v127
	v_mov_b32_e32 v11, v127
	v_mov_b32_e32 v10, v127
	v_mov_b32_e32 v9, v127
	v_mov_b32_e32 v8, v127
	v_mov_b32_e32 v55, v127
	v_mov_b32_e32 v54, v127
	v_mov_b32_e32 v53, v127
	v_mov_b32_e32 v52, v127
	v_mov_b32_e32 v51, v127
	v_mov_b32_e32 v50, v127
	v_mov_b32_e32 v49, v127
	v_mov_b32_e32 v48, v127
	v_mov_b32_e32 v39, v127
	v_mov_b32_e32 v38, v127
	v_mov_b32_e32 v37, v127
	v_mov_b32_e32 v36, v127
	v_mov_b32_e32 v35, v127
	v_mov_b32_e32 v34, v127
	v_mov_b32_e32 v33, v127
	v_mov_b32_e32 v32, v127
	v_mov_b32_e32 v23, v127
	v_mov_b32_e32 v22, v127
	v_mov_b32_e32 v21, v127
	v_mov_b32_e32 v20, v127
	v_mov_b32_e32 v19, v127
	v_mov_b32_e32 v18, v127
	v_mov_b32_e32 v17, v127
	v_mov_b32_e32 v16, v127
	v_mov_b32_e32 v7, v127
	v_mov_b32_e32 v6, v127
	s_waitcnt lgkmcnt(0)
	v_mov_b32_e32 v5, v127
	v_mov_b32_e32 v4, v127
	v_mov_b32_e32 v3, v127
	v_mov_b32_e32 v2, v127
	v_mov_b32_e32 v1, v127
	v_mov_b32_e32 v0, v127
	s_cbranch_vccnz .LBB0_814
	s_add_u32 s61, s26, 0x100
	v_mov_b32_e32 v0, 0
	s_addc_u32 s62, s27, 0
	s_mov_b32 s28, 0
	v_mov_b32_e32 v1, v0
	v_mov_b32_e32 v2, v0
	v_mov_b32_e32 v3, v0
	v_mov_b32_e32 v4, v0
	v_mov_b32_e32 v5, v0
.LBB0_813:
	ds_read_b128 v[144:147], v151
	ds_read_b128 v[156:159], v151 offset:1024
	ds_read_b128 v[160:163], v151 offset:2048
	ds_read_b128 v[164:167], v151 offset:3072
	ds_read_b128 v[168:171], v152
	ds_read_b128 v[172:175], v152 offset:1024
	ds_read_b128 v[176:179], v152 offset:2048
	ds_read_b128 v[182:185], v152 offset:3072
	s_add_i32 s63, s28, 2
	s_add_u32 s26, s24, 0x100
	s_addc_u32 s27, s25, 0
	s_cmp_eq_u32 s54, s28
	s_cselect_b32 s28, s22, s61
	s_cselect_b32 s31, s9, s27
	s_cselect_b32 s30, s8, s26
	s_cselect_b32 s29, s23, s62
	v_lshl_add_u64 v[218:219], s[24:25], 0, v[136:137]
	s_add_i32 m0, s40, 0xc000
	ds_read_b128 v[186:189], v153
	ds_read_b128 v[190:193], v153 offset:1024
	ds_read_b128 v[194:197], v153 offset:2048
	ds_read_b128 v[198:201], v153 offset:3072
	ds_read_b128 v[202:205], v153 offset:4096
	ds_read_b128 v[206:209], v153 offset:5120
	ds_read_b128 v[210:213], v153 offset:6144
	ds_read_b128 v[214:217], v153 offset:7168
	global_load_lds_dwordx4 v[218:219], off
	v_lshl_add_u64 v[218:219], s[24:25], 0, v[138:139]
	s_add_i32 m0, s40, 0xe000
	s_nop 0
	global_load_lds_dwordx4 v[218:219], off
	s_waitcnt vmcnt(8)
	s_waitcnt lgkmcnt(0)
	s_setprio 1
	s_barrier
; #define PG8_STAGE(bufoff, gbase, voff) do { _Pragma("unroll") for (int _i = 0; _i < 2; ++_i) \
;         __builtin_amdgcn_global_load_lds((const unsigned*)((const char*)(gbase) + (voff)[_i]), (LAS unsigned*)(lds + (bufoff) + ldsw + _i * 8192), 16, 0, 0); } while (0)
; #define PG8_LDA(dst, b, h) do { _Pragma("unroll") for (int m = 0; m < 4; ++m) _Pragma("unroll") for (int k = 0; k < 2; ++k) dst[m][k] = *(const LAS bf16x8*)(lds + PG8_SA(b, h) + aoff + m * 2048 + k * 1024); } while (0)
; #define PG8_MMA(ai, bj, At, Bt) do { __builtin_amdgcn_s_setprio(1); _Pragma("unroll") for (int m = 0; m < 4; ++m) _Pragma("unroll") for (int n = 0; n < 2; ++n) _Pragma("unroll") for (int k = 0; k < 2; ++k) \
;         acc[ai][bj][m][n] = __builtin_amdgcn_mfma_f32_16x16x32_bf16(Bt[n][k], At[m][k], acc[ai][bj][m][n], 0, 0, 0); __builtin_amdgcn_s_setprio(0); } while (0)
; #define PG8_WAIT_V(n) asm volatile("s_waitcnt vmcnt(" #n ")" ::: "memory")
; #define PG8_WAIT_L(n) asm volatile("s_waitcnt lgkmcnt(" #n ")" ::: "memory")
; #define PG8_BAR __builtin_amdgcn_s_barrier()
; #define PG8_SCHED __builtin_amdgcn_sched_barrier(0)
; template <class Epi>
; DI void gemm_phase(LAS unsigned char* lds, const Gemm g, const StaticOrder& S, const Epi& E) {
;     ...
;             PG8_WAIT_V(8); PG8_WAIT_L(0); PG8_BAR; PG8_MMA(0, 0, At, B0); PG8_MMA(0, 1, At, B1); PG8_BAR; PG8_SCHED;
;             PG8_LDA(At, 0, 1); PG8_STAGE(PG8_SB(0, 0), b2, voffB); PG8_STAGE(PG8_SB(0, 1), b2 + hstepB, voffB); PG8_STAGE(PG8_SA(0, 0), a2, voffA);
;             PG8_WAIT_V(8); PG8_WAIT_L(0); PG8_BAR; PG8_MMA(1, 0, At, B0); PG8_MMA(1, 1, At, B1); PG8_BAR; PG8_SCHED;
	v_mfma_f32_16x16x32_bf16 v[124:127], v[144:147], v[186:189], v[124:127]
	v_mfma_f32_16x16x32_bf16 v[124:127], v[156:159], v[190:193], v[124:127]
	v_mfma_f32_16x16x32_bf16 v[120:123], v[160:163], v[186:189], v[120:123]
	v_mfma_f32_16x16x32_bf16 v[120:123], v[164:167], v[190:193], v[120:123]
	v_mfma_f32_16x16x32_bf16 v[108:111], v[144:147], v[194:197], v[108:111]
	v_mfma_f32_16x16x32_bf16 v[108:111], v[156:159], v[198:201], v[108:111]
	v_mfma_f32_16x16x32_bf16 v[104:107], v[160:163], v[194:197], v[104:107]
	v_mfma_f32_16x16x32_bf16 v[104:107], v[164:167], v[198:201], v[104:107]
	v_mfma_f32_16x16x32_bf16 v[92:95], v[144:147], v[202:205], v[92:95]
	v_mfma_f32_16x16x32_bf16 v[92:95], v[156:159], v[206:209], v[92:95]
	v_mfma_f32_16x16x32_bf16 v[88:91], v[160:163], v[202:205], v[88:91]
	v_mfma_f32_16x16x32_bf16 v[88:91], v[164:167], v[206:209], v[88:91]
	v_mfma_f32_16x16x32_bf16 v[76:79], v[144:147], v[210:213], v[76:79]
	v_mfma_f32_16x16x32_bf16 v[76:79], v[156:159], v[214:217], v[76:79]
	v_mfma_f32_16x16x32_bf16 v[72:75], v[160:163], v[210:213], v[72:75]
	v_mfma_f32_16x16x32_bf16 v[72:75], v[164:167], v[214:217], v[72:75]
	s_setprio 0
	s_setprio 1
	v_mfma_f32_16x16x32_bf16 v[116:119], v[168:171], v[186:189], v[116:119]
	v_mfma_f32_16x16x32_bf16 v[116:119], v[172:175], v[190:193], v[116:119]
	v_mfma_f32_16x16x32_bf16 v[112:115], v[176:179], v[186:189], v[112:115]
	v_mfma_f32_16x16x32_bf16 v[112:115], v[182:185], v[190:193], v[112:115]
	v_mfma_f32_16x16x32_bf16 v[100:103], v[168:171], v[194:197], v[100:103]
	v_mfma_f32_16x16x32_bf16 v[100:103], v[172:175], v[198:201], v[100:103]
	v_mfma_f32_16x16x32_bf16 v[96:99], v[176:179], v[194:197], v[96:99]
	v_mfma_f32_16x16x32_bf16 v[96:99], v[182:185], v[198:201], v[96:99]
	v_mfma_f32_16x16x32_bf16 v[84:87], v[168:171], v[202:205], v[84:87]
	v_mfma_f32_16x16x32_bf16 v[84:87], v[172:175], v[206:209], v[84:87]
	v_mfma_f32_16x16x32_bf16 v[80:83], v[176:179], v[202:205], v[80:83]
	v_mfma_f32_16x16x32_bf16 v[80:83], v[182:185], v[206:209], v[80:83]
	v_mfma_f32_16x16x32_bf16 v[68:71], v[168:171], v[210:213], v[68:71]
	v_mfma_f32_16x16x32_bf16 v[68:71], v[172:175], v[214:217], v[68:71]
	v_mfma_f32_16x16x32_bf16 v[64:67], v[176:179], v[210:213], v[64:67]
	v_mfma_f32_16x16x32_bf16 v[64:67], v[182:185], v[214:217], v[64:67]
	s_setprio 0
	s_barrier
	s_add_i32 s24, s55, s39
	v_lshl_add_u64 v[218:219], s[28:29], 0, v[130:131]
	s_mov_b32 m0, s24
	ds_read_b128 v[186:189], v153 offset:16384
	ds_read_b128 v[190:193], v153 offset:17408
	ds_read_b128 v[194:197], v153 offset:18432
	ds_read_b128 v[198:201], v153 offset:19456
	ds_read_b128 v[202:205], v153 offset:20480
	ds_read_b128 v[206:209], v153 offset:21504
	ds_read_b128 v[210:213], v153 offset:22528
	ds_read_b128 v[214:217], v153 offset:23552
	global_load_lds_dwordx4 v[218:219], off
	s_add_i32 m0, s24, 0x2000
	s_add_u32 s24, s28, 0x2b0000
	v_lshl_add_u64 v[220:221], s[28:29], 0, v[134:135]
	s_addc_u32 s25, s29, 0
	s_add_i32 s64, s56, s39
	global_load_lds_dwordx4 v[220:221], off
	v_lshl_add_u64 v[222:223], s[24:25], 0, v[130:131]
	s_mov_b32 m0, s64
	v_lshl_add_u64 v[224:225], s[30:31], 0, v[132:133]
	global_load_lds_dwordx4 v[222:223], off
	v_lshl_add_u64 v[222:223], s[24:25], 0, v[134:135]
	s_add_i32 m0, s64, 0x2000
	s_nop 0
	global_load_lds_dwordx4 v[222:223], off
	v_lshl_add_u64 v[222:223], s[30:31], 0, v[128:129]
	s_mov_b32 m0, s40
	s_nop 0
	global_load_lds_dwordx4 v[222:223], off
	s_mov_b32 m0, s41
	s_nop 0
	global_load_lds_dwordx4 v[224:225], off
	s_waitcnt vmcnt(8)
	s_waitcnt lgkmcnt(0)
	s_setprio 1
	s_barrier
	v_mfma_f32_16x16x32_bf16 v[60:63], v[144:147], v[186:189], v[60:63]
	v_mfma_f32_16x16x32_bf16 v[60:63], v[156:159], v[190:193], v[60:63]
	v_mfma_f32_16x16x32_bf16 v[56:59], v[160:163], v[186:189], v[56:59]
	v_mfma_f32_16x16x32_bf16 v[56:59], v[164:167], v[190:193], v[56:59]
	v_mfma_f32_16x16x32_bf16 v[44:47], v[144:147], v[194:197], v[44:47]
	v_mfma_f32_16x16x32_bf16 v[44:47], v[156:159], v[198:201], v[44:47]
	v_mfma_f32_16x16x32_bf16 v[40:43], v[160:163], v[194:197], v[40:43]
	v_mfma_f32_16x16x32_bf16 v[40:43], v[164:167], v[198:201], v[40:43]
	v_mfma_f32_16x16x32_bf16 v[28:31], v[144:147], v[202:205], v[28:31]
	v_mfma_f32_16x16x32_bf16 v[28:31], v[156:159], v[206:209], v[28:31]
	v_mfma_f32_16x16x32_bf16 v[24:27], v[160:163], v[202:205], v[24:27]
	v_mfma_f32_16x16x32_bf16 v[24:27], v[164:167], v[206:209], v[24:27]
	v_mfma_f32_16x16x32_bf16 v[12:15], v[144:147], v[210:213], v[12:15]
	v_mfma_f32_16x16x32_bf16 v[12:15], v[156:159], v[214:217], v[12:15]
	v_mfma_f32_16x16x32_bf16 v[8:11], v[160:163], v[210:213], v[8:11]
	v_mfma_f32_16x16x32_bf16 v[8:11], v[164:167], v[214:217], v[8:11]
	s_setprio 0
	s_setprio 1
	v_mfma_f32_16x16x32_bf16 v[52:55], v[168:171], v[186:189], v[52:55]
	v_mfma_f32_16x16x32_bf16 v[52:55], v[172:175], v[190:193], v[52:55]
	v_mfma_f32_16x16x32_bf16 v[48:51], v[176:179], v[186:189], v[48:51]
	v_mfma_f32_16x16x32_bf16 v[48:51], v[182:185], v[190:193], v[48:51]
	v_mfma_f32_16x16x32_bf16 v[36:39], v[168:171], v[194:197], v[36:39]
	v_mfma_f32_16x16x32_bf16 v[36:39], v[172:175], v[198:201], v[36:39]
	v_mfma_f32_16x16x32_bf16 v[32:35], v[176:179], v[194:197], v[32:35]
	v_mfma_f32_16x16x32_bf16 v[32:35], v[182:185], v[198:201], v[32:35]
	v_mfma_f32_16x16x32_bf16 v[20:23], v[168:171], v[202:205], v[20:23]
	v_mfma_f32_16x16x32_bf16 v[20:23], v[172:175], v[206:209], v[20:23]
	v_mfma_f32_16x16x32_bf16 v[16:19], v[176:179], v[202:205], v[16:19]
	v_mfma_f32_16x16x32_bf16 v[16:19], v[182:185], v[206:209], v[16:19]
	v_mfma_f32_16x16x32_bf16 v[4:7], v[168:171], v[210:213], v[4:7]
	v_mfma_f32_16x16x32_bf16 v[4:7], v[172:175], v[214:217], v[4:7]
	v_mfma_f32_16x16x32_bf16 v[0:3], v[176:179], v[210:213], v[0:3]
	v_mfma_f32_16x16x32_bf16 v[0:3], v[182:185], v[214:217], v[0:3]
	s_setprio 0
	s_barrier
; #define PG8_STAGE(bufoff, gbase, voff) do { _Pragma("unroll") for (int _i = 0; _i < 2; ++_i) \
;         __builtin_amdgcn_global_load_lds((const unsigned*)((const char*)(gbase) + (voff)[_i]), (LAS unsigned*)(lds + (bufoff) + ldsw + _i * 8192), 16, 0, 0); } while (0)
; #define PG8_LDA(dst, b, h) do { _Pragma("unroll") for (int m = 0; m < 4; ++m) _Pragma("unroll") for (int k = 0; k < 2; ++k) dst[m][k] = *(const LAS bf16x8*)(lds + PG8_SA(b, h) + aoff + m * 2048 + k * 1024); } while (0)
; #define PG8_LDB(dst, b, h) do { _Pragma("unroll") for (int n = 0; n < 2; ++n) _Pragma("unroll") for (int k = 0; k < 2; ++k) dst[n][k] = *(const LAS bf16x8*)(lds + PG8_SB(b, h) + boff + n * 2048 + k * 1024); } while (0)
; #define PG8_MMA(ai, bj, At, Bt) do { __builtin_amdgcn_s_setprio(1); _Pragma("unroll") for (int m = 0; m < 4; ++m) _Pragma("unroll") for (int n = 0; n < 2; ++n) _Pragma("unroll") for (int k = 0; k < 2; ++k) \
;         acc[ai][bj][m][n] = __builtin_amdgcn_mfma_f32_16x16x32_bf16(Bt[n][k], At[m][k], acc[ai][bj][m][n], 0, 0, 0); __builtin_amdgcn_s_setprio(0); } while (0)
; #define PG8_WAIT_V(n) asm volatile("s_waitcnt vmcnt(" #n ")" ::: "memory")
; #define PG8_WAIT_L(n) asm volatile("s_waitcnt lgkmcnt(" #n ")" ::: "memory")
; #define PG8_BAR __builtin_amdgcn_s_barrier()
; #define PG8_SCHED __builtin_amdgcn_sched_barrier(0)
; template <class Epi>
; DI void gemm_phase(LAS unsigned char* lds, const Gemm g, const StaticOrder& S, const Epi& E) {
;     ...
;             PG8_LDB(B0, 1, 0); PG8_LDB(B1, 1, 1); PG8_SCHED; PG8_LDA(At, 1, 0); PG8_STAGE(PG8_SA(0, 1), a2 + hstepA, voffA);
;             PG8_WAIT_V(8); PG8_WAIT_L(0); PG8_BAR; PG8_MMA(0, 0, At, B0); PG8_MMA(0, 1, At, B1); PG8_BAR; PG8_SCHED;
	s_add_i32 s64, 0, 0x18000
	v_add_u32_e32 v155, s64, v149
	s_add_i32 s65, 0, 0x1c000
	ds_read_b128 v[144:147], v155
	ds_read_b128 v[156:159], v155 offset:1024
	ds_read_b128 v[160:163], v155 offset:2048
	ds_read_b128 v[164:167], v155 offset:3072
	v_add_u32_e32 v155, s65, v149
	ds_read_b128 v[168:171], v155
	ds_read_b128 v[172:175], v155 offset:1024
	ds_read_b128 v[176:179], v155 offset:2048
	ds_read_b128 v[182:185], v155 offset:3072
	s_add_u32 s24, s30, 0x2b0000
	s_addc_u32 s25, s31, 0
	s_mov_b32 m0, s42
	v_lshl_add_u64 v[226:227], s[24:25], 0, v[128:129]
	ds_read_b128 v[186:189], v153 offset:32768
	ds_read_b128 v[190:193], v153 offset:33792
	ds_read_b128 v[194:197], v153 offset:34816
	ds_read_b128 v[198:201], v153 offset:35840
	ds_read_b128 v[202:205], v153 offset:36864
	ds_read_b128 v[206:209], v153 offset:37888
	ds_read_b128 v[210:213], v153 offset:38912
	ds_read_b128 v[214:217], v153 offset:39936
	global_load_lds_dwordx4 v[226:227], off
	v_lshl_add_u64 v[226:227], s[24:25], 0, v[132:133]
	s_mov_b32 m0, s43
	s_nop 0
	global_load_lds_dwordx4 v[226:227], off
	s_waitcnt vmcnt(8)
	s_waitcnt lgkmcnt(0)
	s_setprio 1
	s_barrier
	v_mfma_f32_16x16x32_bf16 v[124:127], v[144:147], v[186:189], v[124:127]
	v_mfma_f32_16x16x32_bf16 v[124:127], v[156:159], v[190:193], v[124:127]
	v_mfma_f32_16x16x32_bf16 v[120:123], v[160:163], v[186:189], v[120:123]
	v_mfma_f32_16x16x32_bf16 v[120:123], v[164:167], v[190:193], v[120:123]
	v_mfma_f32_16x16x32_bf16 v[108:111], v[144:147], v[194:197], v[108:111]
	v_mfma_f32_16x16x32_bf16 v[108:111], v[156:159], v[198:201], v[108:111]
	v_mfma_f32_16x16x32_bf16 v[104:107], v[160:163], v[194:197], v[104:107]
	v_mfma_f32_16x16x32_bf16 v[104:107], v[164:167], v[198:201], v[104:107]
	v_mfma_f32_16x16x32_bf16 v[92:95], v[144:147], v[202:205], v[92:95]
	v_mfma_f32_16x16x32_bf16 v[92:95], v[156:159], v[206:209], v[92:95]
	v_mfma_f32_16x16x32_bf16 v[88:91], v[160:163], v[202:205], v[88:91]
	v_mfma_f32_16x16x32_bf16 v[88:91], v[164:167], v[206:209], v[88:91]
	v_mfma_f32_16x16x32_bf16 v[76:79], v[144:147], v[210:213], v[76:79]
	v_mfma_f32_16x16x32_bf16 v[76:79], v[156:159], v[214:217], v[76:79]
	v_mfma_f32_16x16x32_bf16 v[72:75], v[160:163], v[210:213], v[72:75]
	v_mfma_f32_16x16x32_bf16 v[72:75], v[164:167], v[214:217], v[72:75]
	s_setprio 0
	s_setprio 1
	v_mfma_f32_16x16x32_bf16 v[116:119], v[168:171], v[186:189], v[116:119]
	v_mfma_f32_16x16x32_bf16 v[116:119], v[172:175], v[190:193], v[116:119]
	v_mfma_f32_16x16x32_bf16 v[112:115], v[176:179], v[186:189], v[112:115]
	v_mfma_f32_16x16x32_bf16 v[112:115], v[182:185], v[190:193], v[112:115]
	v_mfma_f32_16x16x32_bf16 v[100:103], v[168:171], v[194:197], v[100:103]
	v_mfma_f32_16x16x32_bf16 v[100:103], v[172:175], v[198:201], v[100:103]
	v_mfma_f32_16x16x32_bf16 v[96:99], v[176:179], v[194:197], v[96:99]
	v_mfma_f32_16x16x32_bf16 v[96:99], v[182:185], v[198:201], v[96:99]
	v_mfma_f32_16x16x32_bf16 v[84:87], v[168:171], v[202:205], v[84:87]
	v_mfma_f32_16x16x32_bf16 v[84:87], v[172:175], v[206:209], v[84:87]
	v_mfma_f32_16x16x32_bf16 v[80:83], v[176:179], v[202:205], v[80:83]
	v_mfma_f32_16x16x32_bf16 v[80:83], v[182:185], v[206:209], v[80:83]
	v_mfma_f32_16x16x32_bf16 v[68:71], v[168:171], v[210:213], v[68:71]
	v_mfma_f32_16x16x32_bf16 v[68:71], v[172:175], v[214:217], v[68:71]
	v_mfma_f32_16x16x32_bf16 v[64:67], v[176:179], v[210:213], v[64:67]
	v_mfma_f32_16x16x32_bf16 v[64:67], v[182:185], v[214:217], v[64:67]
	s_setprio 0
	s_barrier
; #define PG8_STAGE(bufoff, gbase, voff) do { _Pragma("unroll") for (int _i = 0; _i < 2; ++_i) \
;         __builtin_amdgcn_global_load_lds((const unsigned*)((const char*)(gbase) + (voff)[_i]), (LAS unsigned*)(lds + (bufoff) + ldsw + _i * 8192), 16, 0, 0); } while (0)
; #define PG8_LDA(dst, b, h) do { _Pragma("unroll") for (int m = 0; m < 4; ++m) _Pragma("unroll") for (int k = 0; k < 2; ++k) dst[m][k] = *(const LAS bf16x8*)(lds + PG8_SA(b, h) + aoff + m * 2048 + k * 1024); } while (0)
; #define PG8_MMA(ai, bj, At, Bt) do { __builtin_amdgcn_s_setprio(1); _Pragma("unroll") for (int m = 0; m < 4; ++m) _Pragma("unroll") for (int n = 0; n < 2; ++n) _Pragma("unroll") for (int k = 0; k < 2; ++k) \
;         acc[ai][bj][m][n] = __builtin_amdgcn_mfma_f32_16x16x32_bf16(Bt[n][k], At[m][k], acc[ai][bj][m][n], 0, 0, 0); __builtin_amdgcn_s_setprio(0); } while (0)
; #define PG8_WAIT_V(n) asm volatile("s_waitcnt vmcnt(" #n ")" ::: "memory")
; #define PG8_WAIT_L(n) asm volatile("s_waitcnt lgkmcnt(" #n ")" ::: "memory")
; #define PG8_BAR __builtin_amdgcn_s_barrier()
; #define PG8_SCHED __builtin_amdgcn_sched_barrier(0)
; template <class Epi>
; DI void gemm_phase(LAS unsigned char* lds, const Gemm g, const StaticOrder& S, const Epi& E) {
;     ...
;             PG8_LDA(At, 1, 1); PG8_STAGE(PG8_SB(1, 0), b3, voffB); PG8_STAGE(PG8_SB(1, 1), b3 + hstepB, voffB); PG8_STAGE(PG8_SA(1, 0), a3, voffA);
;             PG8_WAIT_V(8); PG8_WAIT_L(0); PG8_BAR; PG8_MMA(1, 0, At, B0); PG8_MMA(1, 1, At, B1); PG8_BAR; PG8_SCHED;
;         }
	s_add_i32 s24, s64, s39
	v_lshl_add_u64 v[218:219], v[218:219], 0, s[16:17]
	s_mov_b32 m0, s24
	ds_read_b128 v[186:189], v153 offset:49152
	ds_read_b128 v[190:193], v153 offset:50176
	ds_read_b128 v[194:197], v153 offset:51200
	ds_read_b128 v[198:201], v153 offset:52224
	ds_read_b128 v[202:205], v153 offset:53248
	ds_read_b128 v[206:209], v153 offset:54272
	ds_read_b128 v[210:213], v153 offset:55296
	ds_read_b128 v[214:217], v153 offset:56320
	global_load_lds_dwordx4 v[218:219], off
	s_add_i32 m0, s24, 0x2000
	s_add_u32 s24, s28, 0x2b0080
	v_lshl_add_u64 v[218:219], v[220:221], 0, s[16:17]
	s_addc_u32 s25, s29, 0
	s_add_i32 s28, s65, s39
	global_load_lds_dwordx4 v[218:219], off
	v_lshl_add_u64 v[218:219], s[24:25], 0, v[130:131]
	s_mov_b32 m0, s28
	s_nop 0
	global_load_lds_dwordx4 v[218:219], off
	v_lshl_add_u64 v[218:219], s[24:25], 0, v[134:135]
	s_add_i32 m0, s28, 0x2000
	s_nop 0
	global_load_lds_dwordx4 v[218:219], off
	v_lshl_add_u64 v[218:219], v[222:223], 0, s[16:17]
	s_mov_b32 m0, s52
	s_nop 0
	global_load_lds_dwordx4 v[218:219], off
	v_lshl_add_u64 v[218:219], v[224:225], 0, s[16:17]
	s_mov_b32 m0, s53
	s_nop 0
	global_load_lds_dwordx4 v[218:219], off
	s_waitcnt vmcnt(8)
	s_waitcnt lgkmcnt(0)
	s_setprio 1
	s_barrier
	v_mfma_f32_16x16x32_bf16 v[60:63], v[144:147], v[186:189], v[60:63]
	v_mfma_f32_16x16x32_bf16 v[60:63], v[156:159], v[190:193], v[60:63]
	v_mfma_f32_16x16x32_bf16 v[56:59], v[160:163], v[186:189], v[56:59]
	v_mfma_f32_16x16x32_bf16 v[56:59], v[164:167], v[190:193], v[56:59]
	v_mfma_f32_16x16x32_bf16 v[44:47], v[144:147], v[194:197], v[44:47]
	v_mfma_f32_16x16x32_bf16 v[44:47], v[156:159], v[198:201], v[44:47]
	v_mfma_f32_16x16x32_bf16 v[40:43], v[160:163], v[194:197], v[40:43]
	v_mfma_f32_16x16x32_bf16 v[40:43], v[164:167], v[198:201], v[40:43]
	v_mfma_f32_16x16x32_bf16 v[28:31], v[144:147], v[202:205], v[28:31]
	v_mfma_f32_16x16x32_bf16 v[28:31], v[156:159], v[206:209], v[28:31]
	v_mfma_f32_16x16x32_bf16 v[24:27], v[160:163], v[202:205], v[24:27]
	v_mfma_f32_16x16x32_bf16 v[24:27], v[164:167], v[206:209], v[24:27]
	v_mfma_f32_16x16x32_bf16 v[12:15], v[144:147], v[210:213], v[12:15]
	v_mfma_f32_16x16x32_bf16 v[12:15], v[156:159], v[214:217], v[12:15]
	v_mfma_f32_16x16x32_bf16 v[8:11], v[160:163], v[210:213], v[8:11]
	v_mfma_f32_16x16x32_bf16 v[8:11], v[164:167], v[214:217], v[8:11]
	s_setprio 0
	s_setprio 1
	v_mfma_f32_16x16x32_bf16 v[52:55], v[168:171], v[186:189], v[52:55]
	v_mfma_f32_16x16x32_bf16 v[52:55], v[172:175], v[190:193], v[52:55]
	v_mfma_f32_16x16x32_bf16 v[48:51], v[176:179], v[186:189], v[48:51]
	v_mfma_f32_16x16x32_bf16 v[48:51], v[182:185], v[190:193], v[48:51]
	v_mfma_f32_16x16x32_bf16 v[36:39], v[168:171], v[194:197], v[36:39]
	v_mfma_f32_16x16x32_bf16 v[36:39], v[172:175], v[198:201], v[36:39]
	v_mfma_f32_16x16x32_bf16 v[32:35], v[176:179], v[194:197], v[32:35]
	v_mfma_f32_16x16x32_bf16 v[32:35], v[182:185], v[198:201], v[32:35]
	v_mfma_f32_16x16x32_bf16 v[20:23], v[168:171], v[202:205], v[20:23]
	v_mfma_f32_16x16x32_bf16 v[20:23], v[172:175], v[206:209], v[20:23]
	v_mfma_f32_16x16x32_bf16 v[16:19], v[176:179], v[202:205], v[16:19]
	v_mfma_f32_16x16x32_bf16 v[16:19], v[182:185], v[206:209], v[16:19]
	v_mfma_f32_16x16x32_bf16 v[4:7], v[168:171], v[210:213], v[4:7]
	v_mfma_f32_16x16x32_bf16 v[4:7], v[172:175], v[214:217], v[4:7]
	v_mfma_f32_16x16x32_bf16 v[0:3], v[176:179], v[210:213], v[0:3]
	v_mfma_f32_16x16x32_bf16 v[0:3], v[182:185], v[214:217], v[0:3]
	s_setprio 0
	s_barrier
	s_add_u32 s61, s61, 0x100
	s_addc_u32 s62, s62, 0
	s_cmp_ge_i32 s63, s51
	s_mov_b64 s[24:25], s[26:27]
	s_mov_b32 s28, s63
	s_cbranch_scc0 .LBB0_813

; #define PG8_STAGE(bufoff, gbase, voff) do { _Pragma("unroll") for (int _i = 0; _i < 2; ++_i) \
;         __builtin_amdgcn_global_load_lds((const unsigned*)((const char*)(gbase) + (voff)[_i]), (LAS unsigned*)(lds + (bufoff) + ldsw + _i * 8192), 16, 0, 0); } while (0)
; #define PG8_WAIT_V(n) asm volatile("s_waitcnt vmcnt(" #n ")" ::: "memory")
; #define PG8_BAR __builtin_amdgcn_s_barrier()
; template <class Epi>
; DI void gemm_phase(LAS unsigned char* lds, const Gemm g, const StaticOrder& S, const Epi& E) {
;     ...
;     f32x4 acc[2][2][4][2];
; #pragma unroll
;     for (int a = 0; a < 2; ++a)
; #pragma unroll
;         for (int b = 0; b < 2; ++b)
; #pragma unroll
;             for (int m = 0; m < 4; ++m)
; #pragma unroll
;                 for (int n = 0; n < 2; ++n) acc[a][b][m][n] = (f32x4){0.f, 0.f, 0.f, 0.f};
;     bf16x8 At[4][2], B0[2][2], B1[2][2];
;     ...
;     const char* cA = (const char*)g.A + (size_t)cur.pm * tstepA + PG8_KOFF(cur); const char* cB = (const char*)g.Bt + (size_t)cur.pn * tstepB + PG8_KOFF(cur);
;     PG8_STAGE(PG8_SB(0, 0), cB, voffB); PG8_STAGE(PG8_SB(0, 1), cB + hstepB, voffB); PG8_STAGE(PG8_SA(0, 0), cA, voffA); PG8_STAGE(PG8_SA(0, 1), cA + hstepA, voffA);
;     if (wr == 1) PG8_BAR;
;     PG8_WAIT_V(2); PG8_BAR;
;     PG8_STAGE(PG8_SB(1, 0), cB + kstep, voffB); PG8_STAGE(PG8_SA(1, 0), cA + kstep, voffA); PG8_STAGE(PG8_SB(1, 1), cB + hstepB + kstep, voffB);
;     PG8_WAIT_V(6); PG8_BAR;
;     for (;;) {
;         const bool has_next = S.next(ui + 1, nxt);
;         const char* nA = has_next ? (const char*)g.A + (size_t)nxt.pm * tstepA + PG8_KOFF(nxt) : cA; const char* nB = has_next ? (const char*)g.Bt + (size_t)nxt.pn * tstepB + PG8_KOFF(nxt) : cB;
;         for (int t = 0; t < nt; t += 2) {
;             const bool last = (t == nt - 2);
;             const char* a1 = cA + (size_t)(t + 1) * kstep;
;             const char* a2 = last ? nA : cA + (size_t)(t + 2) * kstep; const char* b2 = last ? nB : cB + (size_t)(t + 2) * kstep;
;             const char* a3 = a2 + kstep; const char* b3 = b2 + kstep;
.LBB0_970:
	s_ashr_i32 s21, s20, 31
	s_lshl_b64 s[22:23], s[20:21], 21
	s_add_u32 s22, s8, s22
	s_addc_u32 s23, s9, s23
	s_ashr_i32 s19, s18, 31
	s_lshl_b64 s[24:25], s[18:19], 21
	s_add_u32 s24, s36, s24
	v_mov_b32_e32 v127, 0
	s_addc_u32 s25, s37, s25
	s_andn2_b64 vcc, exec, s[14:15]
	v_mov_b32_e32 v126, v127
	v_mov_b32_e32 v125, v127
	v_mov_b32_e32 v124, v127
	v_mov_b32_e32 v123, v127
	v_mov_b32_e32 v122, v127
	v_mov_b32_e32 v121, v127
	v_mov_b32_e32 v120, v127
	v_mov_b32_e32 v111, v127
	v_mov_b32_e32 v110, v127
	v_mov_b32_e32 v109, v127
	v_mov_b32_e32 v108, v127
	v_mov_b32_e32 v107, v127
	v_mov_b32_e32 v106, v127
	v_mov_b32_e32 v105, v127
	v_mov_b32_e32 v104, v127
	v_mov_b32_e32 v95, v127
	v_mov_b32_e32 v94, v127
	v_mov_b32_e32 v93, v127
	v_mov_b32_e32 v92, v127
	v_mov_b32_e32 v91, v127
	v_mov_b32_e32 v90, v127
	v_mov_b32_e32 v89, v127
	v_mov_b32_e32 v88, v127
	v_mov_b32_e32 v79, v127
	v_mov_b32_e32 v78, v127
	v_mov_b32_e32 v77, v127
	v_mov_b32_e32 v76, v127
	v_mov_b32_e32 v75, v127
	v_mov_b32_e32 v74, v127
	v_mov_b32_e32 v73, v127
	v_mov_b32_e32 v72, v127
	v_mov_b32_e32 v119, v127
	v_mov_b32_e32 v118, v127
	v_mov_b32_e32 v117, v127
	v_mov_b32_e32 v116, v127
	v_mov_b32_e32 v115, v127
	v_mov_b32_e32 v114, v127
	v_mov_b32_e32 v113, v127
	v_mov_b32_e32 v112, v127
	v_mov_b32_e32 v103, v127
	v_mov_b32_e32 v102, v127
	v_mov_b32_e32 v101, v127
	v_mov_b32_e32 v100, v127
	v_mov_b32_e32 v99, v127
	v_mov_b32_e32 v98, v127
	v_mov_b32_e32 v97, v127
	v_mov_b32_e32 v96, v127
	v_mov_b32_e32 v87, v127
	v_mov_b32_e32 v86, v127
	v_mov_b32_e32 v85, v127
	v_mov_b32_e32 v84, v127
	v_mov_b32_e32 v83, v127
	v_mov_b32_e32 v82, v127
	v_mov_b32_e32 v81, v127
	v_mov_b32_e32 v80, v127
	v_mov_b32_e32 v71, v127
	v_mov_b32_e32 v70, v127
	v_mov_b32_e32 v69, v127
	v_mov_b32_e32 v68, v127
	v_mov_b32_e32 v67, v127
	v_mov_b32_e32 v66, v127
	v_mov_b32_e32 v65, v127
	v_mov_b32_e32 v64, v127
	v_mov_b32_e32 v63, v127
	v_mov_b32_e32 v62, v127
	v_mov_b32_e32 v61, v127
	v_mov_b32_e32 v60, v127
	v_mov_b32_e32 v59, v127
	v_mov_b32_e32 v58, v127
	v_mov_b32_e32 v57, v127
	v_mov_b32_e32 v56, v127
	v_mov_b32_e32 v47, v127
	v_mov_b32_e32 v46, v127
	v_mov_b32_e32 v45, v127
	v_mov_b32_e32 v44, v127
	v_mov_b32_e32 v43, v127
	v_mov_b32_e32 v42, v127
	v_mov_b32_e32 v41, v127
	v_mov_b32_e32 v40, v127
	v_mov_b32_e32 v31, v127
	v_mov_b32_e32 v30, v127
	v_mov_b32_e32 v29, v127
	v_mov_b32_e32 v28, v127
	v_mov_b32_e32 v27, v127
	v_mov_b32_e32 v26, v127
	v_mov_b32_e32 v25, v127
	v_mov_b32_e32 v24, v127
	v_mov_b32_e32 v15, v127
	v_mov_b32_e32 v14, v127
	v_mov_b32_e32 v13, v127
	v_mov_b32_e32 v12, v127
	v_mov_b32_e32 v11, v127
	v_mov_b32_e32 v10, v127
	v_mov_b32_e32 v9, v127
	v_mov_b32_e32 v8, v127
	v_mov_b32_e32 v55, v127
	v_mov_b32_e32 v54, v127
	v_mov_b32_e32 v53, v127
	v_mov_b32_e32 v52, v127
	v_mov_b32_e32 v51, v127
	v_mov_b32_e32 v50, v127
	v_mov_b32_e32 v49, v127
	v_mov_b32_e32 v48, v127
	v_mov_b32_e32 v39, v127
	v_mov_b32_e32 v38, v127
	v_mov_b32_e32 v37, v127
	v_mov_b32_e32 v36, v127
	v_mov_b32_e32 v35, v127
	v_mov_b32_e32 v34, v127
	v_mov_b32_e32 v33, v127
	v_mov_b32_e32 v32, v127
	v_mov_b32_e32 v23, v127
	v_mov_b32_e32 v22, v127
	v_mov_b32_e32 v21, v127
	v_mov_b32_e32 v20, v127
	v_mov_b32_e32 v19, v127
	v_mov_b32_e32 v18, v127
	v_mov_b32_e32 v17, v127
	v_mov_b32_e32 v16, v127
	v_mov_b32_e32 v7, v127
	v_mov_b32_e32 v6, v127
	v_mov_b32_e32 v5, v127
	v_mov_b32_e32 v4, v127
	v_mov_b32_e32 v3, v127
	v_mov_b32_e32 v2, v127
	v_mov_b32_e32 v1, v127
	v_mov_b32_e32 v0, v127
	s_cbranch_vccnz .LBB0_973
	s_and_b64 s[34:35], s[0:1], exec
	s_cselect_b32 s19, s23, s29
	s_cselect_b32 s21, s22, s28
	s_cselect_b32 s51, s25, s31
	s_cselect_b32 s52, s24, s30
	s_add_u32 s28, s28, 0x100080
	s_addc_u32 s29, s29, 0
	s_add_u32 s53, s30, 0x100
	s_addc_u32 s54, s31, 0
	s_mov_b32 s30, 0
